# merged waits: each R phase's s_waitcnt vmcnt(N) and s_waitcnt lgkmcnt(0) folded into one instruction in all four K-loops
# baseline (speedup 1.0000x reference)
; #define PG8_STAGE(bufoff, gbase, voff) do { _Pragma("unroll") for (int _i = 0; _i < 2; ++_i) \
;         __builtin_amdgcn_global_load_lds((const unsigned*)((const char*)(gbase) + (voff)[_i]), (LAS unsigned*)(lds + (bufoff) + ldsw + _i * 8192), 16, 0, 0); } while (0)
; #define PG8_LDA(dst, b, h) do { _Pragma("unroll") for (int m = 0; m < 4; ++m) _Pragma("unroll") for (int k = 0; k < 2; ++k) dst[m][k] = *(const LAS bf16x8*)(lds + PG8_SA(b, h) + aoff + m * 2048 + k * 1024); } while (0)
; #define PG8_LDB(dst, b, h) do { _Pragma("unroll") for (int n = 0; n < 2; ++n) _Pragma("unroll") for (int k = 0; k < 2; ++k) dst[n][k] = *(const LAS bf16x8*)(lds + PG8_SB(b, h) + boff + n * 2048 + k * 1024); } while (0)
; #define PG8_MMA(ai, bj, At, Bt) do { __builtin_amdgcn_s_setprio(3); _Pragma("unroll") for (int m = 0; m < 4; ++m) _Pragma("unroll") for (int n = 0; n < 2; ++n) _Pragma("unroll") for (int k = 0; k < 2; ++k) \
;         acc[ai][bj][m][n] = __builtin_amdgcn_mfma_f32_16x16x32_bf16(Bt[n][k], At[m][k], acc[ai][bj][m][n], 0, 0, 0); __builtin_amdgcn_s_setprio(0); } while (0)
; #define PG8_WAIT_V(n) asm volatile("s_waitcnt vmcnt(" #n ")" ::: "memory")
; template <class Epi, class Sched, bool ALIGN_EPI = false, bool SP2 = false>
; __device__ __forceinline__ void gemm_phase(LAS unsigned char* lds, const Gemm g, const Sched& S, const Epi& E) {
;     ...
;         for (int t = 0; t < nt; t += 2) {
;             const bool last = (t == nt - 2);
;             const char* a1 = cA + (size_t)(t + 1) * kstep;
;             const char* a2 = last ? nA : cA + (size_t)(t + 2) * kstep; const char* b2 = last ? nB : cB + (size_t)(t + 2) * kstep;
;             const char* a3 = a2 + kstep; const char* b3 = b2 + kstep;
;             if (last && has_next) S.a_ready(nxt);
;             if constexpr (Epi::MID) { if (t == nt / 2) E.mid(acc, cur, wr, wc, fr, fq); }
;             if constexpr (SP2) {
;             PG8_LDB(B0, 0, 0); PG8_LDB(B1, 0, 1); PG8_SCHED; PG8_LDA(At, 0, 0); PG8_STAGE(PG8_SA(1, 1), a1 + hsA, voffA);
;             PG8_WAIT_V(8); PG8_WAIT_L(0); PG8_BAR; PG8_MMA(0, 0, At, B0); PG8_MMA(0, 1, At, B1); PG8_BAR; PG8_SCHED;
;             PG8_LDA(At, 0, 1); PG8_STAGE(PG8_SB(0, 0), b2, voffB); PG8_STAGE(PG8_SB(0, 1), b2 + hsB, voffB); PG8_STAGE(PG8_SA(0, 0), a2, voffA);
;             PG8_WAIT_V(8); PG8_WAIT_L(0); PG8_BAR; PG8_MMA(1, 0, At, B0); PG8_MMA(1, 1, At, B1); PG8_BAR; PG8_SCHED;
.LBB0_64:
	ds_read_b128 v[128:131], v158
	ds_read_b128 v[150:153], v251
	ds_read_b128 v[166:169], v158 offset:2048
	ds_read_b128 v[170:173], v251 offset:2048
	ds_read_b128 v[174:177], v159
	ds_read_b128 v[178:181], v252
	ds_read_b128 v[182:185], v159 offset:2048
	ds_read_b128 v[186:189], v252 offset:2048
	s_add_u32 s6, s4, 0xffefc080
	s_addc_u32 s7, s5, -1
	s_cmp_eq_u32 s91, 60
	s_cselect_b32 s63, s59, s7
	s_cselect_b32 s62, s58, s6
	s_cselect_b32 s7, s61, s90
	s_cselect_b32 s6, s60, s89
	s_sub_u32 s100, s4, 0x104000
	s_subb_u32 s101, s5, 0
	s_mov_b32 m0, s76
	ds_read_b128 v[214:217], v250 offset:4096
	global_load_lds_dwordx4 v132, s[100:101]
	s_mov_b32 m0, s77
	ds_read_b128 v[218:221], v160 offset:6144
	global_load_lds_dwordx4 v136, s[100:101]
	s_add_i32 m0, s68, 0xc000
	ds_read_b128 v[190:193], v160
	ds_read_b128 v[194:197], v250
	ds_read_b128 v[198:201], v160 offset:2048
	ds_read_b128 v[206:209], v250 offset:2048
	ds_read_b128 v[210:213], v160 offset:4096
	global_load_lds_dwordx4 v142, s[4:5]
	s_add_i32 m0, s68, 0xe000
	ds_read_b128 v[222:225], v250 offset:6144
	global_load_lds_dwordx4 v144, s[4:5]
	s_waitcnt vmcnt(8) lgkmcnt(0)
	s_setprio 2
	s_barrier
	v_mfma_f32_16x16x32_bf16 v[124:127], v[128:131], v[190:193], v[124:127]
	v_mfma_f32_16x16x32_bf16 v[124:127], v[150:153], v[194:197], v[124:127]
	v_mfma_f32_16x16x32_bf16 v[120:123], v[166:169], v[190:193], v[120:123]
	v_mfma_f32_16x16x32_bf16 v[120:123], v[170:173], v[194:197], v[120:123]
	v_mfma_f32_16x16x32_bf16 v[108:111], v[128:131], v[198:201], v[108:111]
	v_mfma_f32_16x16x32_bf16 v[108:111], v[150:153], v[206:209], v[108:111]
	v_mfma_f32_16x16x32_bf16 v[104:107], v[166:169], v[198:201], v[104:107]
	v_mfma_f32_16x16x32_bf16 v[104:107], v[170:173], v[206:209], v[104:107]
	v_mfma_f32_16x16x32_bf16 v[92:95], v[128:131], v[210:213], v[92:95]
	v_mfma_f32_16x16x32_bf16 v[92:95], v[150:153], v[214:217], v[92:95]
	v_mfma_f32_16x16x32_bf16 v[88:91], v[166:169], v[210:213], v[88:91]
	v_mfma_f32_16x16x32_bf16 v[88:91], v[170:173], v[214:217], v[88:91]
	v_mfma_f32_16x16x32_bf16 v[76:79], v[128:131], v[218:221], v[76:79]
	v_mfma_f32_16x16x32_bf16 v[76:79], v[150:153], v[222:225], v[76:79]
	v_mfma_f32_16x16x32_bf16 v[72:75], v[166:169], v[218:221], v[72:75]
	v_mfma_f32_16x16x32_bf16 v[72:75], v[170:173], v[222:225], v[72:75]
	s_setprio 0
	s_setprio 2
	v_mfma_f32_16x16x32_bf16 v[116:119], v[174:177], v[190:193], v[116:119]
	v_mfma_f32_16x16x32_bf16 v[116:119], v[178:181], v[194:197], v[116:119]
	v_mfma_f32_16x16x32_bf16 v[112:115], v[182:185], v[190:193], v[112:115]
	v_mfma_f32_16x16x32_bf16 v[112:115], v[186:189], v[194:197], v[112:115]
	v_mfma_f32_16x16x32_bf16 v[100:103], v[174:177], v[198:201], v[100:103]
	v_mfma_f32_16x16x32_bf16 v[100:103], v[178:181], v[206:209], v[100:103]
	v_mfma_f32_16x16x32_bf16 v[96:99], v[182:185], v[198:201], v[96:99]
	v_mfma_f32_16x16x32_bf16 v[96:99], v[186:189], v[206:209], v[96:99]
	v_mfma_f32_16x16x32_bf16 v[84:87], v[174:177], v[210:213], v[84:87]
	v_mfma_f32_16x16x32_bf16 v[84:87], v[178:181], v[214:217], v[84:87]
	v_mfma_f32_16x16x32_bf16 v[80:83], v[182:185], v[210:213], v[80:83]
	v_mfma_f32_16x16x32_bf16 v[80:83], v[186:189], v[214:217], v[80:83]
	v_mfma_f32_16x16x32_bf16 v[68:71], v[174:177], v[218:221], v[68:71]
	v_mfma_f32_16x16x32_bf16 v[68:71], v[178:181], v[222:225], v[68:71]
	v_mfma_f32_16x16x32_bf16 v[64:67], v[182:185], v[218:221], v[64:67]
	s_setprio 3
	s_barrier
	v_mfma_f32_16x16x32_bf16 v[64:67], v[186:189], v[222:225], v[64:67]
	s_setprio 0
	s_add_i32 s92, s82, s67
	s_mov_b32 m0, s92
	ds_read_b128 v[190:193], v160 offset:16384
	ds_read_b128 v[194:197], v250 offset:16384
	ds_read_b128 v[198:201], v160 offset:18432
	ds_read_b128 v[206:209], v250 offset:18432
	ds_read_b128 v[210:213], v160 offset:20480
	ds_read_b128 v[214:217], v250 offset:20480
	global_load_lds_dwordx4 v134, s[6:7]
	s_add_i32 m0, s92, 0x2000
	s_add_u32 s92, s6, 0x41000
	s_addc_u32 s93, s7, 0
	s_add_i32 s94, s83, s67
	global_load_lds_dwordx4 v138, s[6:7]
	s_mov_b32 m0, s94
	ds_read_b128 v[218:221], v160 offset:22528
	global_load_lds_dwordx4 v134, s[92:93]
	s_add_i32 m0, s94, 0x2000
	ds_read_b128 v[222:225], v250 offset:22528
	global_load_lds_dwordx4 v138, s[92:93]
	s_waitcnt vmcnt(6) lgkmcnt(0)
	s_setprio 2
	s_barrier
	v_mfma_f32_16x16x32_bf16 v[60:63], v[128:131], v[190:193], v[60:63]
	v_mfma_f32_16x16x32_bf16 v[60:63], v[150:153], v[194:197], v[60:63]
	v_mfma_f32_16x16x32_bf16 v[56:59], v[166:169], v[190:193], v[56:59]
	v_mfma_f32_16x16x32_bf16 v[56:59], v[170:173], v[194:197], v[56:59]
	v_mfma_f32_16x16x32_bf16 v[44:47], v[128:131], v[198:201], v[44:47]
	v_mfma_f32_16x16x32_bf16 v[44:47], v[150:153], v[206:209], v[44:47]
	v_mfma_f32_16x16x32_bf16 v[40:43], v[166:169], v[198:201], v[40:43]
	v_mfma_f32_16x16x32_bf16 v[40:43], v[170:173], v[206:209], v[40:43]
	v_mfma_f32_16x16x32_bf16 v[28:31], v[128:131], v[210:213], v[28:31]
	v_mfma_f32_16x16x32_bf16 v[28:31], v[150:153], v[214:217], v[28:31]
	v_mfma_f32_16x16x32_bf16 v[24:27], v[166:169], v[210:213], v[24:27]
	v_mfma_f32_16x16x32_bf16 v[24:27], v[170:173], v[214:217], v[24:27]
	v_mfma_f32_16x16x32_bf16 v[12:15], v[128:131], v[218:221], v[12:15]
	v_mfma_f32_16x16x32_bf16 v[12:15], v[150:153], v[222:225], v[12:15]
	v_mfma_f32_16x16x32_bf16 v[8:11], v[166:169], v[218:221], v[8:11]
	v_mfma_f32_16x16x32_bf16 v[8:11], v[170:173], v[222:225], v[8:11]
	s_setprio 0
	s_setprio 2
	v_mfma_f32_16x16x32_bf16 v[52:55], v[174:177], v[190:193], v[52:55]
	v_mfma_f32_16x16x32_bf16 v[52:55], v[178:181], v[194:197], v[52:55]
	v_mfma_f32_16x16x32_bf16 v[48:51], v[182:185], v[190:193], v[48:51]
	v_mfma_f32_16x16x32_bf16 v[48:51], v[186:189], v[194:197], v[48:51]
	v_mfma_f32_16x16x32_bf16 v[36:39], v[174:177], v[198:201], v[36:39]
	v_mfma_f32_16x16x32_bf16 v[36:39], v[178:181], v[206:209], v[36:39]
	v_mfma_f32_16x16x32_bf16 v[32:35], v[182:185], v[198:201], v[32:35]
	v_mfma_f32_16x16x32_bf16 v[32:35], v[186:189], v[206:209], v[32:35]
	v_mfma_f32_16x16x32_bf16 v[20:23], v[174:177], v[210:213], v[20:23]
	v_mfma_f32_16x16x32_bf16 v[20:23], v[178:181], v[214:217], v[20:23]
	v_mfma_f32_16x16x32_bf16 v[16:19], v[182:185], v[210:213], v[16:19]
	v_mfma_f32_16x16x32_bf16 v[16:19], v[186:189], v[214:217], v[16:19]
	v_mfma_f32_16x16x32_bf16 v[4:7], v[174:177], v[218:221], v[4:7]
	v_mfma_f32_16x16x32_bf16 v[4:7], v[178:181], v[222:225], v[4:7]
	v_mfma_f32_16x16x32_bf16 v[0:3], v[182:185], v[218:221], v[0:3]
	s_setprio 3
	s_barrier
; #define PG8_STAGE(bufoff, gbase, voff) do { _Pragma("unroll") for (int _i = 0; _i < 2; ++_i) \
;         __builtin_amdgcn_global_load_lds((const unsigned*)((const char*)(gbase) + (voff)[_i]), (LAS unsigned*)(lds + (bufoff) + ldsw + _i * 8192), 16, 0, 0); } while (0)
; #define PG8_LDA(dst, b, h) do { _Pragma("unroll") for (int m = 0; m < 4; ++m) _Pragma("unroll") for (int k = 0; k < 2; ++k) dst[m][k] = *(const LAS bf16x8*)(lds + PG8_SA(b, h) + aoff + m * 2048 + k * 1024); } while (0)
; #define PG8_LDB(dst, b, h) do { _Pragma("unroll") for (int n = 0; n < 2; ++n) _Pragma("unroll") for (int k = 0; k < 2; ++k) dst[n][k] = *(const LAS bf16x8*)(lds + PG8_SB(b, h) + boff + n * 2048 + k * 1024); } while (0)
; #define PG8_MMA(ai, bj, At, Bt) do { __builtin_amdgcn_s_setprio(3); _Pragma("unroll") for (int m = 0; m < 4; ++m) _Pragma("unroll") for (int n = 0; n < 2; ++n) _Pragma("unroll") for (int k = 0; k < 2; ++k) \
;         acc[ai][bj][m][n] = __builtin_amdgcn_mfma_f32_16x16x32_bf16(Bt[n][k], At[m][k], acc[ai][bj][m][n], 0, 0, 0); __builtin_amdgcn_s_setprio(0); } while (0)
; #define PG8_WAIT_V(n) asm volatile("s_waitcnt vmcnt(" #n ")" ::: "memory")
; #define PG8_WAIT_L(n) asm volatile("s_waitcnt lgkmcnt(" #n ")" ::: "memory")
; template <class Epi, class Sched, bool ALIGN_EPI = false, bool SP2 = false>
; __device__ __forceinline__ void gemm_phase(LAS unsigned char* lds, const Gemm g, const Sched& S, const Epi& E) {
;     ...
;             PG8_WAIT_V(8); PG8_WAIT_L(0); PG8_BAR; PG8_MMA(0, 0, At, B0); PG8_MMA(0, 1, At, B1); PG8_BAR; PG8_SCHED;
;             PG8_LDA(At, 0, 1); PG8_STAGE(PG8_SB(0, 0), b2, voffB); PG8_STAGE(PG8_SB(0, 1), b2 + hsB, voffB); PG8_STAGE(PG8_SA(0, 0), a2, voffA);
;             PG8_WAIT_V(8); PG8_WAIT_L(0); PG8_BAR; PG8_MMA(1, 0, At, B0); PG8_MMA(1, 1, At, B1); PG8_BAR; PG8_SCHED;
;             PG8_LDB(B0, 1, 0); PG8_LDB(B1, 1, 1); PG8_SCHED; PG8_LDA(At, 1, 0); PG8_STAGE(PG8_SA(0, 1), a2 + hsA, voffA);
;             PG8_WAIT_V(8); PG8_WAIT_L(0); PG8_BAR; PG8_MMA(0, 0, At, B0); PG8_MMA(0, 1, At, B1); PG8_BAR; PG8_SCHED;
;             PG8_LDA(At, 1, 1); PG8_STAGE(PG8_SB(1, 0), b3, voffB); PG8_STAGE(PG8_SB(1, 1), b3 + hsB, voffB); PG8_STAGE(PG8_SA(1, 0), a3, voffA);
;             PG8_WAIT_V(8); PG8_WAIT_L(0); PG8_BAR; PG8_MMA(1, 0, At, B0); PG8_MMA(1, 1, At, B1); PG8_BAR; PG8_SCHED;
;     ...
;         if constexpr (ALIGN_EPI) { if (wr == 0) PG8_BAR; }
	v_mfma_f32_16x16x32_bf16 v[0:3], v[186:189], v[222:225], v[0:3]
	s_setprio 0
	s_add_i32 s92, 0, 0x18000
	s_add_i32 s93, 0, 0x1c000
	ds_read_b128 v[128:131], v246
	ds_read_b128 v[150:153], v247
	ds_read_b128 v[166:169], v246 offset:2048
	ds_read_b128 v[170:173], v247 offset:2048
	ds_read_b128 v[174:177], v248
	ds_read_b128 v[178:181], v249
	ds_read_b128 v[182:185], v248 offset:2048
	ds_read_b128 v[186:189], v249 offset:2048
	s_mov_b32 m0, s68
	ds_read_b128 v[214:217], v250 offset:36864
	global_load_lds_dwordx4 v132, s[62:63]
	s_mov_b32 m0, s69
	ds_read_b128 v[218:221], v160 offset:38912
	global_load_lds_dwordx4 v136, s[62:63]
	s_add_u32 s62, s62, 0x104000
	s_addc_u32 s63, s63, 0
	s_mov_b32 m0, s70
	ds_read_b128 v[190:193], v160 offset:32768
	ds_read_b128 v[194:197], v250 offset:32768
	ds_read_b128 v[198:201], v160 offset:34816
	ds_read_b128 v[206:209], v250 offset:34816
	ds_read_b128 v[210:213], v160 offset:36864
	global_load_lds_dwordx4 v132, s[62:63]
	s_mov_b32 m0, s71
	ds_read_b128 v[222:225], v250 offset:38912
	global_load_lds_dwordx4 v136, s[62:63]
	s_waitcnt vmcnt(8) lgkmcnt(0)
	s_setprio 2
	s_barrier
	v_mfma_f32_16x16x32_bf16 v[124:127], v[128:131], v[190:193], v[124:127]
	v_mfma_f32_16x16x32_bf16 v[124:127], v[150:153], v[194:197], v[124:127]
	v_mfma_f32_16x16x32_bf16 v[120:123], v[166:169], v[190:193], v[120:123]
	v_mfma_f32_16x16x32_bf16 v[120:123], v[170:173], v[194:197], v[120:123]
	v_mfma_f32_16x16x32_bf16 v[108:111], v[128:131], v[198:201], v[108:111]
	v_mfma_f32_16x16x32_bf16 v[108:111], v[150:153], v[206:209], v[108:111]
	v_mfma_f32_16x16x32_bf16 v[104:107], v[166:169], v[198:201], v[104:107]
	v_mfma_f32_16x16x32_bf16 v[104:107], v[170:173], v[206:209], v[104:107]
	v_mfma_f32_16x16x32_bf16 v[92:95], v[128:131], v[210:213], v[92:95]
	v_mfma_f32_16x16x32_bf16 v[92:95], v[150:153], v[214:217], v[92:95]
	v_mfma_f32_16x16x32_bf16 v[88:91], v[166:169], v[210:213], v[88:91]
	v_mfma_f32_16x16x32_bf16 v[88:91], v[170:173], v[214:217], v[88:91]
	v_mfma_f32_16x16x32_bf16 v[76:79], v[128:131], v[218:221], v[76:79]
	v_mfma_f32_16x16x32_bf16 v[76:79], v[150:153], v[222:225], v[76:79]
	v_mfma_f32_16x16x32_bf16 v[72:75], v[166:169], v[218:221], v[72:75]
	v_mfma_f32_16x16x32_bf16 v[72:75], v[170:173], v[222:225], v[72:75]
	s_setprio 0
	s_setprio 2
	v_mfma_f32_16x16x32_bf16 v[116:119], v[174:177], v[190:193], v[116:119]
	v_mfma_f32_16x16x32_bf16 v[116:119], v[178:181], v[194:197], v[116:119]
	v_mfma_f32_16x16x32_bf16 v[112:115], v[182:185], v[190:193], v[112:115]
	v_mfma_f32_16x16x32_bf16 v[112:115], v[186:189], v[194:197], v[112:115]
	v_mfma_f32_16x16x32_bf16 v[100:103], v[174:177], v[198:201], v[100:103]
	v_mfma_f32_16x16x32_bf16 v[100:103], v[178:181], v[206:209], v[100:103]
	v_mfma_f32_16x16x32_bf16 v[96:99], v[182:185], v[198:201], v[96:99]
	v_mfma_f32_16x16x32_bf16 v[96:99], v[186:189], v[206:209], v[96:99]
	v_mfma_f32_16x16x32_bf16 v[84:87], v[174:177], v[210:213], v[84:87]
	v_mfma_f32_16x16x32_bf16 v[84:87], v[178:181], v[214:217], v[84:87]
	v_mfma_f32_16x16x32_bf16 v[80:83], v[182:185], v[210:213], v[80:83]
	v_mfma_f32_16x16x32_bf16 v[80:83], v[186:189], v[214:217], v[80:83]
	v_mfma_f32_16x16x32_bf16 v[68:71], v[174:177], v[218:221], v[68:71]
	v_mfma_f32_16x16x32_bf16 v[68:71], v[178:181], v[222:225], v[68:71]
	v_mfma_f32_16x16x32_bf16 v[64:67], v[182:185], v[218:221], v[64:67]
	s_setprio 3
	s_barrier
	v_mfma_f32_16x16x32_bf16 v[64:67], v[186:189], v[222:225], v[64:67]
	s_setprio 0
	s_add_i32 s62, s92, s67
	s_add_u32 s100, s6, s46
	s_addc_u32 s101, s7, s47
	s_mov_b32 m0, s62
	ds_read_b128 v[190:193], v160 offset:49152
	ds_read_b128 v[194:197], v250 offset:49152
	ds_read_b128 v[198:201], v160 offset:51200
	ds_read_b128 v[206:209], v250 offset:51200
	ds_read_b128 v[210:213], v160 offset:53248
	ds_read_b128 v[214:217], v250 offset:53248
	global_load_lds_dwordx4 v134, s[100:101]
	s_add_i32 m0, s62, 0x2000
	s_add_u32 s6, s6, 0x41080
	s_addc_u32 s7, s7, 0
	s_add_i32 s62, s93, s67
	global_load_lds_dwordx4 v138, s[100:101]
	s_mov_b32 m0, s62
	ds_read_b128 v[218:221], v160 offset:55296
	global_load_lds_dwordx4 v134, s[6:7]
	s_add_i32 m0, s62, 0x2000
	ds_read_b128 v[222:225], v250 offset:55296
	global_load_lds_dwordx4 v138, s[6:7]
	s_waitcnt vmcnt(6) lgkmcnt(0)
	s_setprio 2
	s_barrier
	v_mfma_f32_16x16x32_bf16 v[60:63], v[128:131], v[190:193], v[60:63]
	v_mfma_f32_16x16x32_bf16 v[60:63], v[150:153], v[194:197], v[60:63]
	v_mfma_f32_16x16x32_bf16 v[56:59], v[166:169], v[190:193], v[56:59]
	v_mfma_f32_16x16x32_bf16 v[56:59], v[170:173], v[194:197], v[56:59]
	v_mfma_f32_16x16x32_bf16 v[44:47], v[128:131], v[198:201], v[44:47]
	v_mfma_f32_16x16x32_bf16 v[44:47], v[150:153], v[206:209], v[44:47]
	v_mfma_f32_16x16x32_bf16 v[40:43], v[166:169], v[198:201], v[40:43]
	v_mfma_f32_16x16x32_bf16 v[40:43], v[170:173], v[206:209], v[40:43]
	v_mfma_f32_16x16x32_bf16 v[28:31], v[128:131], v[210:213], v[28:31]
	v_mfma_f32_16x16x32_bf16 v[28:31], v[150:153], v[214:217], v[28:31]
	v_mfma_f32_16x16x32_bf16 v[24:27], v[166:169], v[210:213], v[24:27]
	v_mfma_f32_16x16x32_bf16 v[24:27], v[170:173], v[214:217], v[24:27]
	v_mfma_f32_16x16x32_bf16 v[12:15], v[128:131], v[218:221], v[12:15]
	v_mfma_f32_16x16x32_bf16 v[12:15], v[150:153], v[222:225], v[12:15]
	v_mfma_f32_16x16x32_bf16 v[8:11], v[166:169], v[218:221], v[8:11]
	v_mfma_f32_16x16x32_bf16 v[8:11], v[170:173], v[222:225], v[8:11]
	s_setprio 0
	s_setprio 2
	v_mfma_f32_16x16x32_bf16 v[52:55], v[174:177], v[190:193], v[52:55]
	v_mfma_f32_16x16x32_bf16 v[52:55], v[178:181], v[194:197], v[52:55]
	v_mfma_f32_16x16x32_bf16 v[48:51], v[182:185], v[190:193], v[48:51]
	v_mfma_f32_16x16x32_bf16 v[48:51], v[186:189], v[194:197], v[48:51]
	v_mfma_f32_16x16x32_bf16 v[36:39], v[174:177], v[198:201], v[36:39]
	v_mfma_f32_16x16x32_bf16 v[36:39], v[178:181], v[206:209], v[36:39]
	v_mfma_f32_16x16x32_bf16 v[32:35], v[182:185], v[198:201], v[32:35]
	v_mfma_f32_16x16x32_bf16 v[32:35], v[186:189], v[206:209], v[32:35]
	v_mfma_f32_16x16x32_bf16 v[20:23], v[174:177], v[210:213], v[20:23]
	v_mfma_f32_16x16x32_bf16 v[20:23], v[178:181], v[214:217], v[20:23]
	v_mfma_f32_16x16x32_bf16 v[16:19], v[182:185], v[210:213], v[16:19]
	v_mfma_f32_16x16x32_bf16 v[16:19], v[186:189], v[214:217], v[16:19]
	v_mfma_f32_16x16x32_bf16 v[4:7], v[174:177], v[218:221], v[4:7]
	v_mfma_f32_16x16x32_bf16 v[4:7], v[178:181], v[222:225], v[4:7]
	v_mfma_f32_16x16x32_bf16 v[0:3], v[182:185], v[218:221], v[0:3]
	s_setprio 3
	s_barrier
	v_mfma_f32_16x16x32_bf16 v[0:3], v[186:189], v[222:225], v[0:3]
	s_setprio 0
	s_add_i32 s91, s91, 2
	s_add_u32 s4, s4, 0x100
	s_addc_u32 s5, s5, 0
	s_add_u32 s89, s89, 0x100
	s_addc_u32 s90, s90, 0
	s_cmp_gt_u32 s91, 61
	s_cbranch_scc0 .LBB0_64
	s_and_b64 vcc, exec, s[50:51]
	s_cbranch_vccz .LBB0_67
	s_barrier

; #define PG8_STAGE(bufoff, gbase, voff) do { _Pragma("unroll") for (int _i = 0; _i < 2; ++_i) \
;         __builtin_amdgcn_global_load_lds((const unsigned*)((const char*)(gbase) + (voff)[_i]), (LAS unsigned*)(lds + (bufoff) + ldsw + _i * 8192), 16, 0, 0); } while (0)
; #define PG8_LDA(dst, b, h) do { _Pragma("unroll") for (int m = 0; m < 4; ++m) _Pragma("unroll") for (int k = 0; k < 2; ++k) dst[m][k] = *(const LAS bf16x8*)(lds + PG8_SA(b, h) + aoff + m * 2048 + k * 1024); } while (0)
; #define PG8_LDB(dst, b, h) do { _Pragma("unroll") for (int n = 0; n < 2; ++n) _Pragma("unroll") for (int k = 0; k < 2; ++k) dst[n][k] = *(const LAS bf16x8*)(lds + PG8_SB(b, h) + boff + n * 2048 + k * 1024); } while (0)
; #define PG8_MMA(ai, bj, At, Bt) do { __builtin_amdgcn_s_setprio(3); _Pragma("unroll") for (int m = 0; m < 4; ++m) _Pragma("unroll") for (int n = 0; n < 2; ++n) _Pragma("unroll") for (int k = 0; k < 2; ++k) \
;         acc[ai][bj][m][n] = __builtin_amdgcn_mfma_f32_16x16x32_bf16(Bt[n][k], At[m][k], acc[ai][bj][m][n], 0, 0, 0); __builtin_amdgcn_s_setprio(0); } while (0)
; #define PG8_WAIT_V(n) asm volatile("s_waitcnt vmcnt(" #n ")" ::: "memory")
; template <class Epi, class Sched, bool ALIGN_EPI = false, bool SP2 = false>
; __device__ __forceinline__ void gemm_phase(LAS unsigned char* lds, const Gemm g, const Sched& S, const Epi& E) {
;     ...
;         for (int t = 0; t < nt; t += 2) {
;             const bool last = (t == nt - 2);
;             const char* a1 = cA + (size_t)(t + 1) * kstep;
;             const char* a2 = last ? nA : cA + (size_t)(t + 2) * kstep; const char* b2 = last ? nB : cB + (size_t)(t + 2) * kstep;
;             const char* a3 = a2 + kstep; const char* b3 = b2 + kstep;
;             if (last && has_next) S.a_ready(nxt);
;             if constexpr (Epi::MID) { if (t == nt / 2) E.mid(acc, cur, wr, wc, fr, fq); }
;             if constexpr (SP2) {
;             PG8_LDB(B0, 0, 0); PG8_LDB(B1, 0, 1); PG8_SCHED; PG8_LDA(At, 0, 0); PG8_STAGE(PG8_SA(1, 1), a1 + hsA, voffA);
;             PG8_WAIT_V(8); PG8_WAIT_L(0); PG8_BAR; PG8_MMA(0, 0, At, B0); PG8_MMA(0, 1, At, B1); PG8_BAR; PG8_SCHED;
;             PG8_LDA(At, 0, 1); PG8_STAGE(PG8_SB(0, 0), b2, voffB); PG8_STAGE(PG8_SB(0, 1), b2 + hsB, voffB); PG8_STAGE(PG8_SA(0, 0), a2, voffA);
;             PG8_WAIT_V(8); PG8_WAIT_L(0); PG8_BAR; PG8_MMA(1, 0, At, B0); PG8_MMA(1, 1, At, B1); PG8_BAR; PG8_SCHED;
.LBB0_234:
	v_add_u32_e32 v1, s88, v194
	v_xor_b32_e32 v253, 64, v1
	ds_read_b128 v[84:87], v1
	ds_read_b128 v[96:99], v253
	ds_read_b128 v[140:143], v1 offset:2048
	ds_read_b128 v[144:147], v253 offset:2048
	v_add_u32_e32 v1, s89, v194
	v_xor_b32_e32 v253, 64, v1
	s_add_u32 s4, s64, s66
	ds_read_b128 v[152:155], v1
	ds_read_b128 v[156:159], v253
	ds_read_b128 v[160:163], v1 offset:2048
	ds_read_b128 v[182:185], v253 offset:2048
	s_addc_u32 s5, s65, s67
	s_add_u32 s4, s4, 0x100
	s_addc_u32 s5, s5, 0
	s_add_u32 s96, s93, s66
	s_addc_u32 s97, s94, s67
	s_cmpk_eq_i32 s66, 0x1f00
	s_cselect_b32 s9, s59, s5
	s_cselect_b32 s8, s91, s4
	s_cselect_b32 s5, s61, s97
	s_cselect_b32 s4, s60, s96
	s_sub_u32 s100, s66, 0x100000
	s_subb_u32 s101, s67, 0
	v_lshl_add_u64 v[242:243], v[148:149], 0, s[100:101]
	s_mov_b32 m0, s81
	v_lshl_add_u64 v[244:245], v[150:151], 0, s[100:101]
	global_load_lds_dwordx4 v[242:243], off
	s_mov_b32 m0, s82
	ds_read_b128 v[228:231], v198 offset:6144
	global_load_lds_dwordx4 v[244:245], off
	v_lshl_add_u64 v[2:3], v[148:149], 0, s[66:67]
	s_add_i32 m0, s41, 0xc000
	ds_read_b128 v[186:189], v198
	ds_read_b128 v[208:211], v250
	ds_read_b128 v[212:215], v198 offset:2048
	ds_read_b128 v[216:219], v250 offset:2048
	ds_read_b128 v[220:223], v198 offset:4096
	ds_read_b128 v[224:227], v250 offset:4096
	global_load_lds_dwordx4 v[2:3], off
	v_lshl_add_u64 v[2:3], v[150:151], 0, s[66:67]
	s_add_i32 m0, s41, 0xe000
	ds_read_b128 v[232:235], v250 offset:6144
	global_load_lds_dwordx4 v[2:3], off
	s_waitcnt vmcnt(8) lgkmcnt(0)
	s_setprio 2
	s_barrier
	v_mfma_f32_16x16x32_bf16 v[136:139], v[84:87], v[186:189], v[136:139]
	v_mfma_f32_16x16x32_bf16 v[136:139], v[96:99], v[208:211], v[136:139]
	v_mfma_f32_16x16x32_bf16 v[132:135], v[140:143], v[186:189], v[132:135]
	v_mfma_f32_16x16x32_bf16 v[132:135], v[144:147], v[208:211], v[132:135]
	v_mfma_f32_16x16x32_bf16 v[120:123], v[84:87], v[212:215], v[120:123]
	v_mfma_f32_16x16x32_bf16 v[120:123], v[96:99], v[216:219], v[120:123]
	v_mfma_f32_16x16x32_bf16 v[116:119], v[140:143], v[212:215], v[116:119]
	v_mfma_f32_16x16x32_bf16 v[116:119], v[144:147], v[216:219], v[116:119]
	v_mfma_f32_16x16x32_bf16 v[104:107], v[84:87], v[220:223], v[104:107]
	v_mfma_f32_16x16x32_bf16 v[104:107], v[96:99], v[224:227], v[104:107]
	v_mfma_f32_16x16x32_bf16 v[100:103], v[140:143], v[220:223], v[100:103]
	v_mfma_f32_16x16x32_bf16 v[100:103], v[144:147], v[224:227], v[100:103]
	v_mfma_f32_16x16x32_bf16 v[80:83], v[84:87], v[228:231], v[80:83]
	v_mfma_f32_16x16x32_bf16 v[80:83], v[96:99], v[232:235], v[80:83]
	v_mfma_f32_16x16x32_bf16 v[76:79], v[140:143], v[228:231], v[76:79]
	v_mfma_f32_16x16x32_bf16 v[76:79], v[144:147], v[232:235], v[76:79]
	s_setprio 0
	s_setprio 2
	v_mfma_f32_16x16x32_bf16 v[128:131], v[152:155], v[186:189], v[128:131]
	v_mfma_f32_16x16x32_bf16 v[128:131], v[156:159], v[208:211], v[128:131]
	v_mfma_f32_16x16x32_bf16 v[124:127], v[160:163], v[186:189], v[124:127]
	v_mfma_f32_16x16x32_bf16 v[124:127], v[182:185], v[208:211], v[124:127]
	v_mfma_f32_16x16x32_bf16 v[112:115], v[152:155], v[212:215], v[112:115]
	v_mfma_f32_16x16x32_bf16 v[112:115], v[156:159], v[216:219], v[112:115]
	v_mfma_f32_16x16x32_bf16 v[108:111], v[160:163], v[212:215], v[108:111]
	v_mfma_f32_16x16x32_bf16 v[108:111], v[182:185], v[216:219], v[108:111]
	v_mfma_f32_16x16x32_bf16 v[92:95], v[152:155], v[220:223], v[92:95]
	v_mfma_f32_16x16x32_bf16 v[92:95], v[156:159], v[224:227], v[92:95]
	v_mfma_f32_16x16x32_bf16 v[88:91], v[160:163], v[220:223], v[88:91]
	v_mfma_f32_16x16x32_bf16 v[88:91], v[182:185], v[224:227], v[88:91]
	v_mfma_f32_16x16x32_bf16 v[72:75], v[152:155], v[228:231], v[72:75]
	v_mfma_f32_16x16x32_bf16 v[72:75], v[156:159], v[232:235], v[72:75]
	v_mfma_f32_16x16x32_bf16 v[68:71], v[160:163], v[228:231], v[68:71]
	s_setprio 3
	s_barrier
	v_mfma_f32_16x16x32_bf16 v[68:71], v[182:185], v[232:235], v[68:71]
	s_setprio 0
	s_add_i32 s96, s88, s31
	s_mov_b32 m0, s96
	ds_read_b128 v[186:189], v198 offset:16384
	ds_read_b128 v[208:211], v250 offset:16384
	ds_read_b128 v[212:215], v198 offset:18432
	ds_read_b128 v[216:219], v250 offset:18432
	ds_read_b128 v[220:223], v198 offset:20480
	ds_read_b128 v[224:227], v250 offset:20480
	global_load_lds_dwordx4 v166, s[4:5]
	s_add_i32 m0, s96, 0x2000
	s_add_u32 s96, s4, 0x104000
	s_addc_u32 s97, s5, 0
	s_add_i32 s98, s89, s31
	global_load_lds_dwordx4 v170, s[4:5]
	s_mov_b32 m0, s98
	ds_read_b128 v[228:231], v198 offset:22528
	global_load_lds_dwordx4 v166, s[96:97]
	s_add_i32 m0, s98, 0x2000
	ds_read_b128 v[232:235], v250 offset:22528
	global_load_lds_dwordx4 v170, s[96:97]
	s_waitcnt vmcnt(6) lgkmcnt(0)
	s_setprio 2
	s_barrier
; #define PG8_STAGE(bufoff, gbase, voff) do { _Pragma("unroll") for (int _i = 0; _i < 2; ++_i) \
;         __builtin_amdgcn_global_load_lds((const unsigned*)((const char*)(gbase) + (voff)[_i]), (LAS unsigned*)(lds + (bufoff) + ldsw + _i * 8192), 16, 0, 0); } while (0)
; #define PG8_LDA(dst, b, h) do { _Pragma("unroll") for (int m = 0; m < 4; ++m) _Pragma("unroll") for (int k = 0; k < 2; ++k) dst[m][k] = *(const LAS bf16x8*)(lds + PG8_SA(b, h) + aoff + m * 2048 + k * 1024); } while (0)
; #define PG8_LDB(dst, b, h) do { _Pragma("unroll") for (int n = 0; n < 2; ++n) _Pragma("unroll") for (int k = 0; k < 2; ++k) dst[n][k] = *(const LAS bf16x8*)(lds + PG8_SB(b, h) + boff + n * 2048 + k * 1024); } while (0)
; #define PG8_MMA(ai, bj, At, Bt) do { __builtin_amdgcn_s_setprio(3); _Pragma("unroll") for (int m = 0; m < 4; ++m) _Pragma("unroll") for (int n = 0; n < 2; ++n) _Pragma("unroll") for (int k = 0; k < 2; ++k) \
;         acc[ai][bj][m][n] = __builtin_amdgcn_mfma_f32_16x16x32_bf16(Bt[n][k], At[m][k], acc[ai][bj][m][n], 0, 0, 0); __builtin_amdgcn_s_setprio(0); } while (0)
; #define PG8_WAIT_V(n) asm volatile("s_waitcnt vmcnt(" #n ")" ::: "memory")
; #define PG8_WAIT_L(n) asm volatile("s_waitcnt lgkmcnt(" #n ")" ::: "memory")
; #define PG8_BAR __builtin_amdgcn_s_barrier()
; #define PG8_SCHED __builtin_amdgcn_sched_barrier(0)
; template <class Epi, class Sched, bool ALIGN_EPI = false, bool SP2 = false>
; __device__ __forceinline__ void gemm_phase(LAS unsigned char* lds, const Gemm g, const Sched& S, const Epi& E) {
;     ...
;             PG8_WAIT_V(8); PG8_WAIT_L(0); PG8_BAR; PG8_MMA(0, 0, At, B0); PG8_MMA(0, 1, At, B1); PG8_BAR; PG8_SCHED;
;             PG8_LDA(At, 0, 1); PG8_STAGE(PG8_SB(0, 0), b2, voffB); PG8_STAGE(PG8_SB(0, 1), b2 + hsB, voffB); PG8_STAGE(PG8_SA(0, 0), a2, voffA);
;             PG8_WAIT_V(8); PG8_WAIT_L(0); PG8_BAR; PG8_MMA(1, 0, At, B0); PG8_MMA(1, 1, At, B1); PG8_BAR; PG8_SCHED;
;             PG8_LDB(B0, 1, 0); PG8_LDB(B1, 1, 1); PG8_SCHED; PG8_LDA(At, 1, 0); PG8_STAGE(PG8_SA(0, 1), a2 + hsA, voffA);
;             PG8_WAIT_V(8); PG8_WAIT_L(0); PG8_BAR; PG8_MMA(0, 0, At, B0); PG8_MMA(0, 1, At, B1); PG8_BAR; PG8_SCHED;
;             PG8_LDA(At, 1, 1); PG8_STAGE(PG8_SB(1, 0), b3, voffB); PG8_STAGE(PG8_SB(1, 1), b3 + hsB, voffB); PG8_STAGE(PG8_SA(1, 0), a3, voffA);
	v_mfma_f32_16x16x32_bf16 v[64:67], v[84:87], v[186:189], v[64:67]
	v_mfma_f32_16x16x32_bf16 v[64:67], v[96:99], v[208:211], v[64:67]
	v_mfma_f32_16x16x32_bf16 v[60:63], v[140:143], v[186:189], v[60:63]
	v_mfma_f32_16x16x32_bf16 v[60:63], v[144:147], v[208:211], v[60:63]
	v_mfma_f32_16x16x32_bf16 v[48:51], v[84:87], v[212:215], v[48:51]
	v_mfma_f32_16x16x32_bf16 v[48:51], v[96:99], v[216:219], v[48:51]
	v_mfma_f32_16x16x32_bf16 v[44:47], v[140:143], v[212:215], v[44:47]
	v_mfma_f32_16x16x32_bf16 v[44:47], v[144:147], v[216:219], v[44:47]
	v_mfma_f32_16x16x32_bf16 v[32:35], v[84:87], v[220:223], v[32:35]
	v_mfma_f32_16x16x32_bf16 v[32:35], v[96:99], v[224:227], v[32:35]
	v_mfma_f32_16x16x32_bf16 v[28:31], v[140:143], v[220:223], v[28:31]
	v_mfma_f32_16x16x32_bf16 v[28:31], v[144:147], v[224:227], v[28:31]
	v_mfma_f32_16x16x32_bf16 v[16:19], v[84:87], v[228:231], v[16:19]
	v_mfma_f32_16x16x32_bf16 v[16:19], v[96:99], v[232:235], v[16:19]
	v_mfma_f32_16x16x32_bf16 v[12:15], v[140:143], v[228:231], v[12:15]
	v_mfma_f32_16x16x32_bf16 v[12:15], v[144:147], v[232:235], v[12:15]
	s_setprio 0
	s_setprio 2
	v_mfma_f32_16x16x32_bf16 v[56:59], v[152:155], v[186:189], v[56:59]
	v_mfma_f32_16x16x32_bf16 v[56:59], v[156:159], v[208:211], v[56:59]
	v_mfma_f32_16x16x32_bf16 v[52:55], v[160:163], v[186:189], v[52:55]
	v_mfma_f32_16x16x32_bf16 v[52:55], v[182:185], v[208:211], v[52:55]
	v_mfma_f32_16x16x32_bf16 v[40:43], v[152:155], v[212:215], v[40:43]
	v_mfma_f32_16x16x32_bf16 v[40:43], v[156:159], v[216:219], v[40:43]
	v_mfma_f32_16x16x32_bf16 v[36:39], v[160:163], v[212:215], v[36:39]
	v_mfma_f32_16x16x32_bf16 v[36:39], v[182:185], v[216:219], v[36:39]
	v_mfma_f32_16x16x32_bf16 v[24:27], v[152:155], v[220:223], v[24:27]
	v_mfma_f32_16x16x32_bf16 v[24:27], v[156:159], v[224:227], v[24:27]
	v_mfma_f32_16x16x32_bf16 v[20:23], v[160:163], v[220:223], v[20:23]
	v_mfma_f32_16x16x32_bf16 v[20:23], v[182:185], v[224:227], v[20:23]
	v_mfma_f32_16x16x32_bf16 v[8:11], v[152:155], v[228:231], v[8:11]
	v_mfma_f32_16x16x32_bf16 v[8:11], v[156:159], v[232:235], v[8:11]
	v_mfma_f32_16x16x32_bf16 v[2:5], v[160:163], v[228:231], v[4:7]
	s_setprio 3
	s_barrier
	v_mfma_f32_16x16x32_bf16 v[2:5], v[182:185], v[232:235], v[2:5]
	s_setprio 0
	s_add_i32 s96, 0, 0x18000
	v_add_u32_e32 v1, s96, v194
	v_xor_b32_e32 v253, 64, v1
	s_add_i32 s97, 0, 0x1c000
	ds_read_b128 v[84:87], v1
	ds_read_b128 v[96:99], v253
	ds_read_b128 v[140:143], v1 offset:2048
	ds_read_b128 v[144:147], v253 offset:2048
	v_add_u32_e32 v1, s97, v194
	v_xor_b32_e32 v253, 64, v1
	ds_read_b128 v[152:155], v1
	ds_read_b128 v[156:159], v253
	ds_read_b128 v[160:163], v1 offset:2048
	ds_read_b128 v[182:185], v253 offset:2048
	s_mov_b32 m0, s41
	ds_read_b128 v[224:227], v250 offset:36864
	global_load_lds_dwordx4 v164, s[8:9]
	s_mov_b32 m0, s68
	ds_read_b128 v[228:231], v198 offset:38912
	global_load_lds_dwordx4 v168, s[8:9]
	s_add_u32 s8, s8, 0x100000
	s_addc_u32 s9, s9, 0
	s_mov_b32 m0, s69
	ds_read_b128 v[186:189], v198 offset:32768
	ds_read_b128 v[208:211], v250 offset:32768
	ds_read_b128 v[212:215], v198 offset:34816
	ds_read_b128 v[216:219], v250 offset:34816
	ds_read_b128 v[220:223], v198 offset:36864
	global_load_lds_dwordx4 v164, s[8:9]
	s_mov_b32 m0, s70
	ds_read_b128 v[232:235], v250 offset:38912
	global_load_lds_dwordx4 v168, s[8:9]
	s_waitcnt vmcnt(8) lgkmcnt(0)
	s_setprio 2
	s_barrier
; #define PG8_STAGE(bufoff, gbase, voff) do { _Pragma("unroll") for (int _i = 0; _i < 2; ++_i) \
;         __builtin_amdgcn_global_load_lds((const unsigned*)((const char*)(gbase) + (voff)[_i]), (LAS unsigned*)(lds + (bufoff) + ldsw + _i * 8192), 16, 0, 0); } while (0)
; #define PG8_LDA(dst, b, h) do { _Pragma("unroll") for (int m = 0; m < 4; ++m) _Pragma("unroll") for (int k = 0; k < 2; ++k) dst[m][k] = *(const LAS bf16x8*)(lds + PG8_SA(b, h) + aoff + m * 2048 + k * 1024); } while (0)
; #define PG8_MMA(ai, bj, At, Bt) do { __builtin_amdgcn_s_setprio(3); _Pragma("unroll") for (int m = 0; m < 4; ++m) _Pragma("unroll") for (int n = 0; n < 2; ++n) _Pragma("unroll") for (int k = 0; k < 2; ++k) \
;         acc[ai][bj][m][n] = __builtin_amdgcn_mfma_f32_16x16x32_bf16(Bt[n][k], At[m][k], acc[ai][bj][m][n], 0, 0, 0); __builtin_amdgcn_s_setprio(0); } while (0)
; #define PG8_WAIT_V(n) asm volatile("s_waitcnt vmcnt(" #n ")" ::: "memory")
; #define PG8_WAIT_L(n) asm volatile("s_waitcnt lgkmcnt(" #n ")" ::: "memory")
; #define PG8_BAR __builtin_amdgcn_s_barrier()
; #define PG8_SCHED __builtin_amdgcn_sched_barrier(0)
; template <class Epi, class Sched, bool ALIGN_EPI = false, bool SP2 = false>
; __device__ __forceinline__ void gemm_phase(LAS unsigned char* lds, const Gemm g, const Sched& S, const Epi& E) {
;     ...
;             PG8_WAIT_V(8); PG8_WAIT_L(0); PG8_BAR; PG8_MMA(0, 0, At, B0); PG8_MMA(0, 1, At, B1); PG8_BAR; PG8_SCHED;
;             PG8_LDA(At, 1, 1); PG8_STAGE(PG8_SB(1, 0), b3, voffB); PG8_STAGE(PG8_SB(1, 1), b3 + hsB, voffB); PG8_STAGE(PG8_SA(1, 0), a3, voffA);
;             PG8_WAIT_V(8); PG8_WAIT_L(0); PG8_BAR; PG8_MMA(1, 0, At, B0); PG8_MMA(1, 1, At, B1); PG8_BAR; PG8_SCHED;
	v_mfma_f32_16x16x32_bf16 v[136:139], v[84:87], v[186:189], v[136:139]
	v_mfma_f32_16x16x32_bf16 v[136:139], v[96:99], v[208:211], v[136:139]
	v_mfma_f32_16x16x32_bf16 v[132:135], v[140:143], v[186:189], v[132:135]
	v_mfma_f32_16x16x32_bf16 v[132:135], v[144:147], v[208:211], v[132:135]
	v_mfma_f32_16x16x32_bf16 v[120:123], v[84:87], v[212:215], v[120:123]
	v_mfma_f32_16x16x32_bf16 v[120:123], v[96:99], v[216:219], v[120:123]
	v_mfma_f32_16x16x32_bf16 v[116:119], v[140:143], v[212:215], v[116:119]
	v_mfma_f32_16x16x32_bf16 v[116:119], v[144:147], v[216:219], v[116:119]
	v_mfma_f32_16x16x32_bf16 v[104:107], v[84:87], v[220:223], v[104:107]
	v_mfma_f32_16x16x32_bf16 v[104:107], v[96:99], v[224:227], v[104:107]
	v_mfma_f32_16x16x32_bf16 v[100:103], v[140:143], v[220:223], v[100:103]
	v_mfma_f32_16x16x32_bf16 v[100:103], v[144:147], v[224:227], v[100:103]
	v_mfma_f32_16x16x32_bf16 v[80:83], v[84:87], v[228:231], v[80:83]
	v_mfma_f32_16x16x32_bf16 v[80:83], v[96:99], v[232:235], v[80:83]
	v_mfma_f32_16x16x32_bf16 v[76:79], v[140:143], v[228:231], v[76:79]
	v_mfma_f32_16x16x32_bf16 v[76:79], v[144:147], v[232:235], v[76:79]
	s_setprio 0
	s_setprio 2
	v_mfma_f32_16x16x32_bf16 v[128:131], v[152:155], v[186:189], v[128:131]
	v_mfma_f32_16x16x32_bf16 v[128:131], v[156:159], v[208:211], v[128:131]
	v_mfma_f32_16x16x32_bf16 v[124:127], v[160:163], v[186:189], v[124:127]
	v_mfma_f32_16x16x32_bf16 v[124:127], v[182:185], v[208:211], v[124:127]
	v_mfma_f32_16x16x32_bf16 v[112:115], v[152:155], v[212:215], v[112:115]
	v_mfma_f32_16x16x32_bf16 v[112:115], v[156:159], v[216:219], v[112:115]
	v_mfma_f32_16x16x32_bf16 v[108:111], v[160:163], v[212:215], v[108:111]
	v_mfma_f32_16x16x32_bf16 v[108:111], v[182:185], v[216:219], v[108:111]
	v_mfma_f32_16x16x32_bf16 v[92:95], v[152:155], v[220:223], v[92:95]
	v_mfma_f32_16x16x32_bf16 v[92:95], v[156:159], v[224:227], v[92:95]
	v_mfma_f32_16x16x32_bf16 v[88:91], v[160:163], v[220:223], v[88:91]
	v_mfma_f32_16x16x32_bf16 v[88:91], v[182:185], v[224:227], v[88:91]
	v_mfma_f32_16x16x32_bf16 v[72:75], v[152:155], v[228:231], v[72:75]
	v_mfma_f32_16x16x32_bf16 v[72:75], v[156:159], v[232:235], v[72:75]
	v_mfma_f32_16x16x32_bf16 v[68:71], v[160:163], v[228:231], v[68:71]
	s_setprio 3
	s_barrier
	v_mfma_f32_16x16x32_bf16 v[68:71], v[182:185], v[232:235], v[68:71]
	s_setprio 0
	s_add_i32 s8, s96, s31
	s_add_u32 s100, s4, s24
	s_addc_u32 s101, s5, s25
	s_mov_b32 m0, s8
	ds_read_b128 v[186:189], v198 offset:49152
	ds_read_b128 v[208:211], v250 offset:49152
	ds_read_b128 v[212:215], v198 offset:51200
	ds_read_b128 v[216:219], v250 offset:51200
	ds_read_b128 v[220:223], v198 offset:53248
	ds_read_b128 v[224:227], v250 offset:53248
	global_load_lds_dwordx4 v166, s[100:101]
	s_add_i32 m0, s8, 0x2000
	s_add_u32 s4, s4, 0x104080
	s_addc_u32 s5, s5, 0
	s_add_i32 s8, s97, s31
	global_load_lds_dwordx4 v170, s[100:101]
	s_mov_b32 m0, s8
	ds_read_b128 v[228:231], v198 offset:55296
	global_load_lds_dwordx4 v166, s[4:5]
	s_add_i32 m0, s8, 0x2000
	ds_read_b128 v[232:235], v250 offset:55296
	global_load_lds_dwordx4 v170, s[4:5]
	s_waitcnt vmcnt(6) lgkmcnt(0)
	s_setprio 2
	s_barrier
	v_mfma_f32_16x16x32_bf16 v[64:67], v[84:87], v[186:189], v[64:67]
	v_mfma_f32_16x16x32_bf16 v[64:67], v[96:99], v[208:211], v[64:67]
	v_mfma_f32_16x16x32_bf16 v[60:63], v[140:143], v[186:189], v[60:63]
	v_mfma_f32_16x16x32_bf16 v[60:63], v[144:147], v[208:211], v[60:63]
	v_mfma_f32_16x16x32_bf16 v[48:51], v[84:87], v[212:215], v[48:51]
	v_mfma_f32_16x16x32_bf16 v[48:51], v[96:99], v[216:219], v[48:51]
	v_mfma_f32_16x16x32_bf16 v[44:47], v[140:143], v[212:215], v[44:47]
	v_mfma_f32_16x16x32_bf16 v[44:47], v[144:147], v[216:219], v[44:47]
	v_mfma_f32_16x16x32_bf16 v[32:35], v[84:87], v[220:223], v[32:35]
	v_mfma_f32_16x16x32_bf16 v[32:35], v[96:99], v[224:227], v[32:35]
	v_mfma_f32_16x16x32_bf16 v[28:31], v[140:143], v[220:223], v[28:31]
	v_mfma_f32_16x16x32_bf16 v[28:31], v[144:147], v[224:227], v[28:31]
	v_mfma_f32_16x16x32_bf16 v[16:19], v[84:87], v[228:231], v[16:19]
	v_mfma_f32_16x16x32_bf16 v[16:19], v[96:99], v[232:235], v[16:19]
	v_mfma_f32_16x16x32_bf16 v[12:15], v[140:143], v[228:231], v[12:15]
	v_mfma_f32_16x16x32_bf16 v[12:15], v[144:147], v[232:235], v[12:15]
	s_setprio 0
	s_setprio 2
	v_mfma_f32_16x16x32_bf16 v[56:59], v[152:155], v[186:189], v[56:59]
	v_mfma_f32_16x16x32_bf16 v[56:59], v[156:159], v[208:211], v[56:59]
	v_mfma_f32_16x16x32_bf16 v[52:55], v[160:163], v[186:189], v[52:55]
	v_mfma_f32_16x16x32_bf16 v[52:55], v[182:185], v[208:211], v[52:55]
	v_mfma_f32_16x16x32_bf16 v[40:43], v[152:155], v[212:215], v[40:43]
	v_mfma_f32_16x16x32_bf16 v[40:43], v[156:159], v[216:219], v[40:43]
	v_mfma_f32_16x16x32_bf16 v[36:39], v[160:163], v[212:215], v[36:39]
	v_mfma_f32_16x16x32_bf16 v[36:39], v[182:185], v[216:219], v[36:39]
	v_mfma_f32_16x16x32_bf16 v[24:27], v[152:155], v[220:223], v[24:27]
	v_mfma_f32_16x16x32_bf16 v[24:27], v[156:159], v[224:227], v[24:27]
	v_mfma_f32_16x16x32_bf16 v[20:23], v[160:163], v[220:223], v[20:23]
	v_mfma_f32_16x16x32_bf16 v[20:23], v[182:185], v[224:227], v[20:23]
	v_mfma_f32_16x16x32_bf16 v[6:9], v[152:155], v[228:231], v[8:11]
	v_mfma_f32_16x16x32_bf16 v[8:11], v[156:159], v[232:235], v[6:9]
	v_mfma_f32_16x16x32_bf16 v[2:5], v[160:163], v[228:231], v[2:5]
	s_setprio 3
	s_barrier
	v_mfma_f32_16x16x32_bf16 v[4:7], v[182:185], v[232:235], v[2:5]
	s_setprio 0
	s_add_i32 s95, s95, 2
	s_add_u32 s66, s66, 0x100
	s_addc_u32 s67, s67, 0
	s_cmp_gt_u32 s95, 61
	s_cbranch_scc1 .LBB0_237

; #define PG8_STAGE(bufoff, gbase, voff) do { _Pragma("unroll") for (int _i = 0; _i < 2; ++_i) \
;         __builtin_amdgcn_global_load_lds((const unsigned*)((const char*)(gbase) + (voff)[_i]), (LAS unsigned*)(lds + (bufoff) + ldsw + _i * 8192), 16, 0, 0); } while (0)
; #define PG8_LDA(dst, b, h) do { _Pragma("unroll") for (int m = 0; m < 4; ++m) _Pragma("unroll") for (int k = 0; k < 2; ++k) dst[m][k] = *(const LAS bf16x8*)(lds + PG8_SA(b, h) + aoff + m * 2048 + k * 1024); } while (0)
; #define PG8_LDB(dst, b, h) do { _Pragma("unroll") for (int n = 0; n < 2; ++n) _Pragma("unroll") for (int k = 0; k < 2; ++k) dst[n][k] = *(const LAS bf16x8*)(lds + PG8_SB(b, h) + boff + n * 2048 + k * 1024); } while (0)
; #define PG8_MMA(ai, bj, At, Bt) do { __builtin_amdgcn_s_setprio(3); _Pragma("unroll") for (int m = 0; m < 4; ++m) _Pragma("unroll") for (int n = 0; n < 2; ++n) _Pragma("unroll") for (int k = 0; k < 2; ++k) \
;         acc[ai][bj][m][n] = __builtin_amdgcn_mfma_f32_16x16x32_bf16(Bt[n][k], At[m][k], acc[ai][bj][m][n], 0, 0, 0); __builtin_amdgcn_s_setprio(0); } while (0)
; #define PG8_WAIT_V(n) asm volatile("s_waitcnt vmcnt(" #n ")" ::: "memory")
; template <class Epi, class Sched, bool ALIGN_EPI = false, bool SP2 = false>
; __device__ __forceinline__ void gemm_phase(LAS unsigned char* lds, const Gemm g, const Sched& S, const Epi& E) {
;     ...
;         for (int t = 0; t < nt; t += 2) {
;             const bool last = (t == nt - 2);
;             const char* a1 = cA + (size_t)(t + 1) * kstep;
;             const char* a2 = last ? nA : cA + (size_t)(t + 2) * kstep; const char* b2 = last ? nB : cB + (size_t)(t + 2) * kstep;
;             const char* a3 = a2 + kstep; const char* b3 = b2 + kstep;
;             if (last && has_next) S.a_ready(nxt);
;             if constexpr (Epi::MID) { if (t == nt / 2) E.mid(acc, cur, wr, wc, fr, fq); }
;             if constexpr (SP2) {
;             PG8_LDB(B0, 0, 0); PG8_LDB(B1, 0, 1); PG8_SCHED; PG8_LDA(At, 0, 0); PG8_STAGE(PG8_SA(1, 1), a1 + hsA, voffA);
;             PG8_WAIT_V(8); PG8_WAIT_L(0); PG8_BAR; PG8_MMA(0, 0, At, B0); PG8_MMA(0, 1, At, B1); PG8_BAR; PG8_SCHED;
;             PG8_LDA(At, 0, 1); PG8_STAGE(PG8_SB(0, 0), b2, voffB); PG8_STAGE(PG8_SB(0, 1), b2 + hsB, voffB); PG8_STAGE(PG8_SA(0, 0), a2, voffA);
;             PG8_WAIT_V(8); PG8_WAIT_L(0); PG8_BAR; PG8_MMA(1, 0, At, B0); PG8_MMA(1, 1, At, B1); PG8_BAR; PG8_SCHED;
.LBB0_309:
	ds_read_b128 v[112:115], v175
	ds_read_b128 v[132:135], v251
	ds_read_b128 v[136:139], v175 offset:2048
	ds_read_b128 v[140:143], v251 offset:2048
	ds_read_b128 v[144:147], v176
	ds_read_b128 v[148:151], v252
	ds_read_b128 v[184:187], v176 offset:2048
	ds_read_b128 v[188:191], v252 offset:2048
	s_add_u32 s24, s4, 0xffefc080
	s_addc_u32 s25, s5, -1
	s_cmp_eq_u32 s73, 60
	s_cselect_b32 s27, s11, s25
	s_cselect_b32 s26, s10, s24
	s_cselect_b32 s25, s21, s72
	s_cselect_b32 s24, s20, s71
	s_sub_u32 s100, s4, 0x104000
	s_subb_u32 s101, s5, 0
	s_mov_b32 m0, s42
	ds_read_b128 v[218:221], v250 offset:4096
	global_load_lds_dwordx4 v152, s[100:101]
	s_mov_b32 m0, s43
	ds_read_b128 v[222:225], v177 offset:6144
	global_load_lds_dwordx4 v156, s[100:101]
	s_add_i32 m0, s36, 0xc000
	ds_read_b128 v[192:195], v177
	ds_read_b128 v[196:199], v250
	ds_read_b128 v[206:209], v177 offset:2048
	ds_read_b128 v[210:213], v250 offset:2048
	ds_read_b128 v[214:217], v177 offset:4096
	global_load_lds_dwordx4 v164, s[4:5]
	s_add_i32 m0, s36, 0xe000
	ds_read_b128 v[226:229], v250 offset:6144
	global_load_lds_dwordx4 v166, s[4:5]
	s_waitcnt vmcnt(8) lgkmcnt(0)
	s_setprio 2
	s_barrier
	v_mfma_f32_16x16x32_bf16 v[128:131], v[112:115], v[192:195], v[128:131]
	v_mfma_f32_16x16x32_bf16 v[128:131], v[132:135], v[196:199], v[128:131]
	v_mfma_f32_16x16x32_bf16 v[124:127], v[136:139], v[192:195], v[124:127]
	v_mfma_f32_16x16x32_bf16 v[124:127], v[140:143], v[196:199], v[124:127]
	v_mfma_f32_16x16x32_bf16 v[108:111], v[112:115], v[206:209], v[108:111]
	v_mfma_f32_16x16x32_bf16 v[108:111], v[132:135], v[210:213], v[108:111]
	v_mfma_f32_16x16x32_bf16 v[104:107], v[136:139], v[206:209], v[104:107]
	v_mfma_f32_16x16x32_bf16 v[104:107], v[140:143], v[210:213], v[104:107]
	v_mfma_f32_16x16x32_bf16 v[92:95], v[112:115], v[214:217], v[92:95]
	v_mfma_f32_16x16x32_bf16 v[92:95], v[132:135], v[218:221], v[92:95]
	v_mfma_f32_16x16x32_bf16 v[88:91], v[136:139], v[214:217], v[88:91]
	v_mfma_f32_16x16x32_bf16 v[88:91], v[140:143], v[218:221], v[88:91]
	v_mfma_f32_16x16x32_bf16 v[76:79], v[112:115], v[222:225], v[76:79]
	v_mfma_f32_16x16x32_bf16 v[76:79], v[132:135], v[226:229], v[76:79]
	v_mfma_f32_16x16x32_bf16 v[72:75], v[136:139], v[222:225], v[72:75]
	v_mfma_f32_16x16x32_bf16 v[72:75], v[140:143], v[226:229], v[72:75]
	s_setprio 0
	s_setprio 2
	v_mfma_f32_16x16x32_bf16 v[120:123], v[144:147], v[192:195], v[120:123]
	v_mfma_f32_16x16x32_bf16 v[120:123], v[148:151], v[196:199], v[120:123]
	v_mfma_f32_16x16x32_bf16 v[116:119], v[184:187], v[192:195], v[116:119]
	v_mfma_f32_16x16x32_bf16 v[116:119], v[188:191], v[196:199], v[116:119]
	v_mfma_f32_16x16x32_bf16 v[100:103], v[144:147], v[206:209], v[100:103]
	v_mfma_f32_16x16x32_bf16 v[100:103], v[148:151], v[210:213], v[100:103]
	v_mfma_f32_16x16x32_bf16 v[96:99], v[184:187], v[206:209], v[96:99]
	v_mfma_f32_16x16x32_bf16 v[96:99], v[188:191], v[210:213], v[96:99]
	v_mfma_f32_16x16x32_bf16 v[84:87], v[144:147], v[214:217], v[84:87]
	v_mfma_f32_16x16x32_bf16 v[84:87], v[148:151], v[218:221], v[84:87]
	v_mfma_f32_16x16x32_bf16 v[80:83], v[184:187], v[214:217], v[80:83]
	v_mfma_f32_16x16x32_bf16 v[80:83], v[188:191], v[218:221], v[80:83]
	v_mfma_f32_16x16x32_bf16 v[68:71], v[144:147], v[222:225], v[68:71]
	v_mfma_f32_16x16x32_bf16 v[68:71], v[148:151], v[226:229], v[68:71]
	v_mfma_f32_16x16x32_bf16 v[64:67], v[184:187], v[222:225], v[64:67]
	s_setprio 3
	s_barrier
	v_mfma_f32_16x16x32_bf16 v[64:67], v[188:191], v[226:229], v[64:67]
	s_setprio 0
	s_add_i32 s74, s45, s31
	s_mov_b32 m0, s74
	ds_read_b128 v[192:195], v177 offset:16384
	ds_read_b128 v[196:199], v250 offset:16384
	ds_read_b128 v[206:209], v177 offset:18432
	ds_read_b128 v[210:213], v250 offset:18432
	ds_read_b128 v[214:217], v177 offset:20480
	ds_read_b128 v[218:221], v250 offset:20480
	global_load_lds_dwordx4 v154, s[24:25]
	s_add_i32 m0, s74, 0x2000
	s_add_u32 s74, s24, 0x41000
	s_addc_u32 s75, s25, 0
	s_add_i32 s78, s46, s31
	global_load_lds_dwordx4 v158, s[24:25]
	s_mov_b32 m0, s78
	ds_read_b128 v[222:225], v177 offset:22528
	global_load_lds_dwordx4 v154, s[74:75]
	s_add_i32 m0, s78, 0x2000
	ds_read_b128 v[226:229], v250 offset:22528
	global_load_lds_dwordx4 v158, s[74:75]
	s_waitcnt vmcnt(6) lgkmcnt(0)
	s_setprio 2
	s_barrier
	v_mfma_f32_16x16x32_bf16 v[60:63], v[112:115], v[192:195], v[60:63]
	v_mfma_f32_16x16x32_bf16 v[60:63], v[132:135], v[196:199], v[60:63]
	v_mfma_f32_16x16x32_bf16 v[56:59], v[136:139], v[192:195], v[56:59]
	v_mfma_f32_16x16x32_bf16 v[56:59], v[140:143], v[196:199], v[56:59]
	v_mfma_f32_16x16x32_bf16 v[44:47], v[112:115], v[206:209], v[44:47]
	v_mfma_f32_16x16x32_bf16 v[44:47], v[132:135], v[210:213], v[44:47]
	v_mfma_f32_16x16x32_bf16 v[40:43], v[136:139], v[206:209], v[40:43]
	v_mfma_f32_16x16x32_bf16 v[40:43], v[140:143], v[210:213], v[40:43]
	v_mfma_f32_16x16x32_bf16 v[28:31], v[112:115], v[214:217], v[28:31]
	v_mfma_f32_16x16x32_bf16 v[28:31], v[132:135], v[218:221], v[28:31]
	v_mfma_f32_16x16x32_bf16 v[24:27], v[136:139], v[214:217], v[24:27]
	v_mfma_f32_16x16x32_bf16 v[24:27], v[140:143], v[218:221], v[24:27]
	v_mfma_f32_16x16x32_bf16 v[12:15], v[112:115], v[222:225], v[12:15]
	v_mfma_f32_16x16x32_bf16 v[12:15], v[132:135], v[226:229], v[12:15]
	v_mfma_f32_16x16x32_bf16 v[8:11], v[136:139], v[222:225], v[8:11]
	v_mfma_f32_16x16x32_bf16 v[8:11], v[140:143], v[226:229], v[8:11]
	s_setprio 0
	s_setprio 2
	v_mfma_f32_16x16x32_bf16 v[52:55], v[144:147], v[192:195], v[52:55]
	v_mfma_f32_16x16x32_bf16 v[52:55], v[148:151], v[196:199], v[52:55]
	v_mfma_f32_16x16x32_bf16 v[48:51], v[184:187], v[192:195], v[48:51]
	v_mfma_f32_16x16x32_bf16 v[48:51], v[188:191], v[196:199], v[48:51]
	v_mfma_f32_16x16x32_bf16 v[36:39], v[144:147], v[206:209], v[36:39]
	v_mfma_f32_16x16x32_bf16 v[36:39], v[148:151], v[210:213], v[36:39]
	v_mfma_f32_16x16x32_bf16 v[32:35], v[184:187], v[206:209], v[32:35]
	v_mfma_f32_16x16x32_bf16 v[32:35], v[188:191], v[210:213], v[32:35]
	v_mfma_f32_16x16x32_bf16 v[20:23], v[144:147], v[214:217], v[20:23]
	v_mfma_f32_16x16x32_bf16 v[20:23], v[148:151], v[218:221], v[20:23]
	v_mfma_f32_16x16x32_bf16 v[16:19], v[184:187], v[214:217], v[16:19]
	v_mfma_f32_16x16x32_bf16 v[16:19], v[188:191], v[218:221], v[16:19]
	v_mfma_f32_16x16x32_bf16 v[4:7], v[144:147], v[222:225], v[4:7]
	v_mfma_f32_16x16x32_bf16 v[4:7], v[148:151], v[226:229], v[4:7]
	v_mfma_f32_16x16x32_bf16 v[0:3], v[184:187], v[222:225], v[0:3]
	s_setprio 3
	s_barrier
; #define PG8_STAGE(bufoff, gbase, voff) do { _Pragma("unroll") for (int _i = 0; _i < 2; ++_i) \
;         __builtin_amdgcn_global_load_lds((const unsigned*)((const char*)(gbase) + (voff)[_i]), (LAS unsigned*)(lds + (bufoff) + ldsw + _i * 8192), 16, 0, 0); } while (0)
; #define PG8_LDA(dst, b, h) do { _Pragma("unroll") for (int m = 0; m < 4; ++m) _Pragma("unroll") for (int k = 0; k < 2; ++k) dst[m][k] = *(const LAS bf16x8*)(lds + PG8_SA(b, h) + aoff + m * 2048 + k * 1024); } while (0)
; #define PG8_LDB(dst, b, h) do { _Pragma("unroll") for (int n = 0; n < 2; ++n) _Pragma("unroll") for (int k = 0; k < 2; ++k) dst[n][k] = *(const LAS bf16x8*)(lds + PG8_SB(b, h) + boff + n * 2048 + k * 1024); } while (0)
; #define PG8_MMA(ai, bj, At, Bt) do { __builtin_amdgcn_s_setprio(3); _Pragma("unroll") for (int m = 0; m < 4; ++m) _Pragma("unroll") for (int n = 0; n < 2; ++n) _Pragma("unroll") for (int k = 0; k < 2; ++k) \
;         acc[ai][bj][m][n] = __builtin_amdgcn_mfma_f32_16x16x32_bf16(Bt[n][k], At[m][k], acc[ai][bj][m][n], 0, 0, 0); __builtin_amdgcn_s_setprio(0); } while (0)
; #define PG8_WAIT_V(n) asm volatile("s_waitcnt vmcnt(" #n ")" ::: "memory")
; #define PG8_WAIT_L(n) asm volatile("s_waitcnt lgkmcnt(" #n ")" ::: "memory")
; template <class Epi, class Sched, bool ALIGN_EPI = false, bool SP2 = false>
; __device__ __forceinline__ void gemm_phase(LAS unsigned char* lds, const Gemm g, const Sched& S, const Epi& E) {
;     ...
;             PG8_WAIT_V(8); PG8_WAIT_L(0); PG8_BAR; PG8_MMA(0, 0, At, B0); PG8_MMA(0, 1, At, B1); PG8_BAR; PG8_SCHED;
;             PG8_LDA(At, 0, 1); PG8_STAGE(PG8_SB(0, 0), b2, voffB); PG8_STAGE(PG8_SB(0, 1), b2 + hsB, voffB); PG8_STAGE(PG8_SA(0, 0), a2, voffA);
;             PG8_WAIT_V(8); PG8_WAIT_L(0); PG8_BAR; PG8_MMA(1, 0, At, B0); PG8_MMA(1, 1, At, B1); PG8_BAR; PG8_SCHED;
;             PG8_LDB(B0, 1, 0); PG8_LDB(B1, 1, 1); PG8_SCHED; PG8_LDA(At, 1, 0); PG8_STAGE(PG8_SA(0, 1), a2 + hsA, voffA);
;             PG8_WAIT_V(8); PG8_WAIT_L(0); PG8_BAR; PG8_MMA(0, 0, At, B0); PG8_MMA(0, 1, At, B1); PG8_BAR; PG8_SCHED;
;             PG8_LDA(At, 1, 1); PG8_STAGE(PG8_SB(1, 0), b3, voffB); PG8_STAGE(PG8_SB(1, 1), b3 + hsB, voffB); PG8_STAGE(PG8_SA(1, 0), a3, voffA);
;             PG8_WAIT_V(8); PG8_WAIT_L(0); PG8_BAR; PG8_MMA(1, 0, At, B0); PG8_MMA(1, 1, At, B1); PG8_BAR; PG8_SCHED;
;     ...
;         if constexpr (ALIGN_EPI) { if (wr == 0) PG8_BAR; }
	v_mfma_f32_16x16x32_bf16 v[0:3], v[188:191], v[226:229], v[0:3]
	s_setprio 0
	s_add_i32 s74, 0, 0x18000
	s_add_i32 s75, 0, 0x1c000
	ds_read_b128 v[112:115], v246
	ds_read_b128 v[132:135], v247
	ds_read_b128 v[136:139], v246 offset:2048
	ds_read_b128 v[140:143], v247 offset:2048
	ds_read_b128 v[144:147], v248
	ds_read_b128 v[148:151], v249
	ds_read_b128 v[184:187], v248 offset:2048
	ds_read_b128 v[188:191], v249 offset:2048
	s_mov_b32 m0, s36
	ds_read_b128 v[218:221], v250 offset:36864
	global_load_lds_dwordx4 v152, s[26:27]
	s_mov_b32 m0, s37
	ds_read_b128 v[222:225], v177 offset:38912
	global_load_lds_dwordx4 v156, s[26:27]
	s_add_u32 s26, s26, 0x104000
	s_addc_u32 s27, s27, 0
	s_mov_b32 m0, s38
	ds_read_b128 v[192:195], v177 offset:32768
	ds_read_b128 v[196:199], v250 offset:32768
	ds_read_b128 v[206:209], v177 offset:34816
	ds_read_b128 v[210:213], v250 offset:34816
	ds_read_b128 v[214:217], v177 offset:36864
	global_load_lds_dwordx4 v152, s[26:27]
	s_mov_b32 m0, s39
	ds_read_b128 v[226:229], v250 offset:38912
	global_load_lds_dwordx4 v156, s[26:27]
	s_waitcnt vmcnt(8) lgkmcnt(0)
	s_setprio 2
	s_barrier
	v_mfma_f32_16x16x32_bf16 v[128:131], v[112:115], v[192:195], v[128:131]
	v_mfma_f32_16x16x32_bf16 v[128:131], v[132:135], v[196:199], v[128:131]
	v_mfma_f32_16x16x32_bf16 v[124:127], v[136:139], v[192:195], v[124:127]
	v_mfma_f32_16x16x32_bf16 v[124:127], v[140:143], v[196:199], v[124:127]
	v_mfma_f32_16x16x32_bf16 v[108:111], v[112:115], v[206:209], v[108:111]
	v_mfma_f32_16x16x32_bf16 v[108:111], v[132:135], v[210:213], v[108:111]
	v_mfma_f32_16x16x32_bf16 v[104:107], v[136:139], v[206:209], v[104:107]
	v_mfma_f32_16x16x32_bf16 v[104:107], v[140:143], v[210:213], v[104:107]
	v_mfma_f32_16x16x32_bf16 v[92:95], v[112:115], v[214:217], v[92:95]
	v_mfma_f32_16x16x32_bf16 v[92:95], v[132:135], v[218:221], v[92:95]
	v_mfma_f32_16x16x32_bf16 v[88:91], v[136:139], v[214:217], v[88:91]
	v_mfma_f32_16x16x32_bf16 v[88:91], v[140:143], v[218:221], v[88:91]
	v_mfma_f32_16x16x32_bf16 v[76:79], v[112:115], v[222:225], v[76:79]
	v_mfma_f32_16x16x32_bf16 v[76:79], v[132:135], v[226:229], v[76:79]
	v_mfma_f32_16x16x32_bf16 v[72:75], v[136:139], v[222:225], v[72:75]
	v_mfma_f32_16x16x32_bf16 v[72:75], v[140:143], v[226:229], v[72:75]
	s_setprio 0
	s_setprio 2
	v_mfma_f32_16x16x32_bf16 v[120:123], v[144:147], v[192:195], v[120:123]
	v_mfma_f32_16x16x32_bf16 v[120:123], v[148:151], v[196:199], v[120:123]
	v_mfma_f32_16x16x32_bf16 v[116:119], v[184:187], v[192:195], v[116:119]
	v_mfma_f32_16x16x32_bf16 v[116:119], v[188:191], v[196:199], v[116:119]
	v_mfma_f32_16x16x32_bf16 v[100:103], v[144:147], v[206:209], v[100:103]
	v_mfma_f32_16x16x32_bf16 v[100:103], v[148:151], v[210:213], v[100:103]
	v_mfma_f32_16x16x32_bf16 v[96:99], v[184:187], v[206:209], v[96:99]
	v_mfma_f32_16x16x32_bf16 v[96:99], v[188:191], v[210:213], v[96:99]
	v_mfma_f32_16x16x32_bf16 v[84:87], v[144:147], v[214:217], v[84:87]
	v_mfma_f32_16x16x32_bf16 v[84:87], v[148:151], v[218:221], v[84:87]
	v_mfma_f32_16x16x32_bf16 v[80:83], v[184:187], v[214:217], v[80:83]
	v_mfma_f32_16x16x32_bf16 v[80:83], v[188:191], v[218:221], v[80:83]
	v_mfma_f32_16x16x32_bf16 v[68:71], v[144:147], v[222:225], v[68:71]
	v_mfma_f32_16x16x32_bf16 v[68:71], v[148:151], v[226:229], v[68:71]
	v_mfma_f32_16x16x32_bf16 v[64:67], v[184:187], v[222:225], v[64:67]
	s_setprio 3
	s_barrier
	v_mfma_f32_16x16x32_bf16 v[64:67], v[188:191], v[226:229], v[64:67]
	s_setprio 0
	s_add_i32 s26, s74, s31
	s_add_u32 s100, s24, s14
	s_addc_u32 s101, s25, s15
	s_mov_b32 m0, s26
	ds_read_b128 v[192:195], v177 offset:49152
	ds_read_b128 v[196:199], v250 offset:49152
	ds_read_b128 v[206:209], v177 offset:51200
	ds_read_b128 v[210:213], v250 offset:51200
	ds_read_b128 v[214:217], v177 offset:53248
	ds_read_b128 v[218:221], v250 offset:53248
	global_load_lds_dwordx4 v154, s[100:101]
	s_add_i32 m0, s26, 0x2000
	s_add_u32 s24, s24, 0x41080
	s_addc_u32 s25, s25, 0
	s_add_i32 s26, s75, s31
	global_load_lds_dwordx4 v158, s[100:101]
	s_mov_b32 m0, s26
	ds_read_b128 v[222:225], v177 offset:55296
	global_load_lds_dwordx4 v154, s[24:25]
	s_add_i32 m0, s26, 0x2000
	ds_read_b128 v[226:229], v250 offset:55296
	global_load_lds_dwordx4 v158, s[24:25]
	s_waitcnt vmcnt(6) lgkmcnt(0)
	s_setprio 2
	s_barrier
	v_mfma_f32_16x16x32_bf16 v[60:63], v[112:115], v[192:195], v[60:63]
	v_mfma_f32_16x16x32_bf16 v[60:63], v[132:135], v[196:199], v[60:63]
	v_mfma_f32_16x16x32_bf16 v[56:59], v[136:139], v[192:195], v[56:59]
	v_mfma_f32_16x16x32_bf16 v[56:59], v[140:143], v[196:199], v[56:59]
	v_mfma_f32_16x16x32_bf16 v[44:47], v[112:115], v[206:209], v[44:47]
	v_mfma_f32_16x16x32_bf16 v[44:47], v[132:135], v[210:213], v[44:47]
	v_mfma_f32_16x16x32_bf16 v[40:43], v[136:139], v[206:209], v[40:43]
	v_mfma_f32_16x16x32_bf16 v[40:43], v[140:143], v[210:213], v[40:43]
	v_mfma_f32_16x16x32_bf16 v[28:31], v[112:115], v[214:217], v[28:31]
	v_mfma_f32_16x16x32_bf16 v[28:31], v[132:135], v[218:221], v[28:31]
	v_mfma_f32_16x16x32_bf16 v[24:27], v[136:139], v[214:217], v[24:27]
	v_mfma_f32_16x16x32_bf16 v[24:27], v[140:143], v[218:221], v[24:27]
	v_mfma_f32_16x16x32_bf16 v[12:15], v[112:115], v[222:225], v[12:15]
	v_mfma_f32_16x16x32_bf16 v[12:15], v[132:135], v[226:229], v[12:15]
	v_mfma_f32_16x16x32_bf16 v[8:11], v[136:139], v[222:225], v[8:11]
	v_mfma_f32_16x16x32_bf16 v[8:11], v[140:143], v[226:229], v[8:11]
	s_setprio 0
	s_setprio 2
	v_mfma_f32_16x16x32_bf16 v[52:55], v[144:147], v[192:195], v[52:55]
	v_mfma_f32_16x16x32_bf16 v[52:55], v[148:151], v[196:199], v[52:55]
	v_mfma_f32_16x16x32_bf16 v[48:51], v[184:187], v[192:195], v[48:51]
	v_mfma_f32_16x16x32_bf16 v[48:51], v[188:191], v[196:199], v[48:51]
	v_mfma_f32_16x16x32_bf16 v[36:39], v[144:147], v[206:209], v[36:39]
	v_mfma_f32_16x16x32_bf16 v[36:39], v[148:151], v[210:213], v[36:39]
	v_mfma_f32_16x16x32_bf16 v[32:35], v[184:187], v[206:209], v[32:35]
	v_mfma_f32_16x16x32_bf16 v[32:35], v[188:191], v[210:213], v[32:35]
	v_mfma_f32_16x16x32_bf16 v[20:23], v[144:147], v[214:217], v[20:23]
	v_mfma_f32_16x16x32_bf16 v[20:23], v[148:151], v[218:221], v[20:23]
	v_mfma_f32_16x16x32_bf16 v[16:19], v[184:187], v[214:217], v[16:19]
	v_mfma_f32_16x16x32_bf16 v[16:19], v[188:191], v[218:221], v[16:19]
	v_mfma_f32_16x16x32_bf16 v[4:7], v[144:147], v[222:225], v[4:7]
	v_mfma_f32_16x16x32_bf16 v[4:7], v[148:151], v[226:229], v[4:7]
	v_mfma_f32_16x16x32_bf16 v[0:3], v[184:187], v[222:225], v[0:3]
	s_setprio 3
	s_barrier
	v_mfma_f32_16x16x32_bf16 v[0:3], v[188:191], v[226:229], v[0:3]
	s_setprio 0
	s_add_i32 s73, s73, 2
	s_add_u32 s4, s4, 0x100
	s_addc_u32 s5, s5, 0
	s_add_u32 s71, s71, 0x100
	s_addc_u32 s72, s72, 0
	s_cmp_gt_u32 s73, 61
	s_cbranch_scc0 .LBB0_309
	s_and_b64 vcc, exec, s[16:17]
	s_cbranch_vccz .LBB0_312
	s_barrier

; #define PG8_STAGE(bufoff, gbase, voff) do { _Pragma("unroll") for (int _i = 0; _i < 2; ++_i) \
;         __builtin_amdgcn_global_load_lds((const unsigned*)((const char*)(gbase) + (voff)[_i]), (LAS unsigned*)(lds + (bufoff) + ldsw + _i * 8192), 16, 0, 0); } while (0)
; #define PG8_LDA(dst, b, h) do { _Pragma("unroll") for (int m = 0; m < 4; ++m) _Pragma("unroll") for (int k = 0; k < 2; ++k) dst[m][k] = *(const LAS bf16x8*)(lds + PG8_SA(b, h) + aoff + m * 2048 + k * 1024); } while (0)
; #define PG8_LDB(dst, b, h) do { _Pragma("unroll") for (int n = 0; n < 2; ++n) _Pragma("unroll") for (int k = 0; k < 2; ++k) dst[n][k] = *(const LAS bf16x8*)(lds + PG8_SB(b, h) + boff + n * 2048 + k * 1024); } while (0)
; #define PG8_MMA(ai, bj, At, Bt) do { __builtin_amdgcn_s_setprio(3); _Pragma("unroll") for (int m = 0; m < 4; ++m) _Pragma("unroll") for (int n = 0; n < 2; ++n) _Pragma("unroll") for (int k = 0; k < 2; ++k) \
;         acc[ai][bj][m][n] = __builtin_amdgcn_mfma_f32_16x16x32_bf16(Bt[n][k], At[m][k], acc[ai][bj][m][n], 0, 0, 0); __builtin_amdgcn_s_setprio(0); } while (0)
; #define PG8_WAIT_V(n) asm volatile("s_waitcnt vmcnt(" #n ")" ::: "memory")
; template <class Epi, class Sched, bool ALIGN_EPI = false, bool SP2 = false>
; __device__ __forceinline__ void gemm_phase(LAS unsigned char* lds, const Gemm g, const Sched& S, const Epi& E) {
;     ...
;         for (int t = 0; t < nt; t += 2) {
;             const bool last = (t == nt - 2);
;             const char* a1 = cA + (size_t)(t + 1) * kstep;
;             const char* a2 = last ? nA : cA + (size_t)(t + 2) * kstep; const char* b2 = last ? nB : cB + (size_t)(t + 2) * kstep;
;             const char* a3 = a2 + kstep; const char* b3 = b2 + kstep;
;             if (last && has_next) S.a_ready(nxt);
;             if constexpr (Epi::MID) { if (t == nt / 2) E.mid(acc, cur, wr, wc, fr, fq); }
;             if constexpr (SP2) {
;             PG8_LDB(B0, 0, 0); PG8_LDB(B1, 0, 1); PG8_SCHED; PG8_LDA(At, 0, 0); PG8_STAGE(PG8_SA(1, 1), a1 + hsA, voffA);
;             PG8_WAIT_V(8); PG8_WAIT_L(0); PG8_BAR; PG8_MMA(0, 0, At, B0); PG8_MMA(0, 1, At, B1); PG8_BAR; PG8_SCHED;
;             PG8_LDA(At, 0, 1); PG8_STAGE(PG8_SB(0, 0), b2, voffB); PG8_STAGE(PG8_SB(0, 1), b2 + hsB, voffB); PG8_STAGE(PG8_SA(0, 0), a2, voffA);
;             PG8_WAIT_V(8); PG8_WAIT_L(0); PG8_BAR; PG8_MMA(1, 0, At, B0); PG8_MMA(1, 1, At, B1); PG8_BAR; PG8_SCHED;
.LBB0_350:
	ds_read_b128 v[140:143], v149
	ds_read_b128 v[156:159], v251
	ds_read_b128 v[160:163], v149 offset:2048
	ds_read_b128 v[164:167], v251 offset:2048
	ds_read_b128 v[168:171], v150
	ds_read_b128 v[172:175], v252
	ds_read_b128 v[176:179], v150 offset:2048
	ds_read_b128 v[180:183], v252 offset:2048
	s_add_u32 s16, s14, 0xffbfc080
	s_addc_u32 s17, s15, -1
	s_cmpk_eq_i32 s50, 0xfc
	s_cselect_b32 s21, s5, s17
	s_cselect_b32 s20, s4, s16
	s_cselect_b32 s17, s13, s49
	s_cselect_b32 s16, s12, s48
	s_sub_u32 s100, s14, 0x404000
	s_subb_u32 s101, s15, 0
	s_mov_b32 m0, s33
	ds_read_b128 v[204:207], v250 offset:4096
	global_load_lds_dwordx4 v128, s[100:101]
	s_mov_b32 m0, s38
	ds_read_b128 v[208:211], v151 offset:6144
	global_load_lds_dwordx4 v130, s[100:101]
	s_add_i32 m0, s26, 0xc000
	ds_read_b128 v[184:187], v151
	ds_read_b128 v[188:191], v250
	ds_read_b128 v[192:195], v151 offset:2048
	ds_read_b128 v[196:199], v250 offset:2048
	ds_read_b128 v[200:203], v151 offset:4096
	global_load_lds_dwordx4 v132, s[14:15]
	s_add_i32 m0, s26, 0xe000
	ds_read_b128 v[212:215], v250 offset:6144
	global_load_lds_dwordx4 v134, s[14:15]
	s_waitcnt vmcnt(8) lgkmcnt(0)
	s_setprio 2
	s_barrier
	v_mfma_f32_16x16x32_bf16 v[124:127], v[140:143], v[184:187], v[124:127]
	v_mfma_f32_16x16x32_bf16 v[124:127], v[156:159], v[188:191], v[124:127]
	v_mfma_f32_16x16x32_bf16 v[120:123], v[160:163], v[184:187], v[120:123]
	v_mfma_f32_16x16x32_bf16 v[120:123], v[164:167], v[188:191], v[120:123]
	v_mfma_f32_16x16x32_bf16 v[108:111], v[140:143], v[192:195], v[108:111]
	v_mfma_f32_16x16x32_bf16 v[108:111], v[156:159], v[196:199], v[108:111]
	v_mfma_f32_16x16x32_bf16 v[104:107], v[160:163], v[192:195], v[104:107]
	v_mfma_f32_16x16x32_bf16 v[104:107], v[164:167], v[196:199], v[104:107]
	v_mfma_f32_16x16x32_bf16 v[92:95], v[140:143], v[200:203], v[92:95]
	v_mfma_f32_16x16x32_bf16 v[92:95], v[156:159], v[204:207], v[92:95]
	v_mfma_f32_16x16x32_bf16 v[88:91], v[160:163], v[200:203], v[88:91]
	v_mfma_f32_16x16x32_bf16 v[88:91], v[164:167], v[204:207], v[88:91]
	v_mfma_f32_16x16x32_bf16 v[76:79], v[140:143], v[208:211], v[76:79]
	v_mfma_f32_16x16x32_bf16 v[76:79], v[156:159], v[212:215], v[76:79]
	v_mfma_f32_16x16x32_bf16 v[72:75], v[160:163], v[208:211], v[72:75]
	v_mfma_f32_16x16x32_bf16 v[72:75], v[164:167], v[212:215], v[72:75]
	s_setprio 0
	s_setprio 2
	v_mfma_f32_16x16x32_bf16 v[116:119], v[168:171], v[184:187], v[116:119]
	v_mfma_f32_16x16x32_bf16 v[116:119], v[172:175], v[188:191], v[116:119]
	v_mfma_f32_16x16x32_bf16 v[112:115], v[176:179], v[184:187], v[112:115]
	v_mfma_f32_16x16x32_bf16 v[112:115], v[180:183], v[188:191], v[112:115]
	v_mfma_f32_16x16x32_bf16 v[100:103], v[168:171], v[192:195], v[100:103]
	v_mfma_f32_16x16x32_bf16 v[100:103], v[172:175], v[196:199], v[100:103]
	v_mfma_f32_16x16x32_bf16 v[96:99], v[176:179], v[192:195], v[96:99]
	v_mfma_f32_16x16x32_bf16 v[96:99], v[180:183], v[196:199], v[96:99]
	v_mfma_f32_16x16x32_bf16 v[84:87], v[168:171], v[200:203], v[84:87]
	v_mfma_f32_16x16x32_bf16 v[84:87], v[172:175], v[204:207], v[84:87]
	v_mfma_f32_16x16x32_bf16 v[80:83], v[176:179], v[200:203], v[80:83]
	v_mfma_f32_16x16x32_bf16 v[80:83], v[180:183], v[204:207], v[80:83]
	v_mfma_f32_16x16x32_bf16 v[68:71], v[168:171], v[208:211], v[68:71]
	v_mfma_f32_16x16x32_bf16 v[68:71], v[172:175], v[212:215], v[68:71]
	s_setprio 3
	s_barrier
	v_mfma_f32_16x16x32_bf16 v[64:67], v[176:179], v[208:211], v[64:67]
	v_mfma_f32_16x16x32_bf16 v[64:67], v[180:183], v[212:215], v[64:67]
	s_setprio 0
	s_add_i32 s51, s41, s25
	s_mov_b32 m0, s51
	ds_read_b128 v[184:187], v151 offset:16384
	ds_read_b128 v[188:191], v250 offset:16384
	ds_read_b128 v[192:195], v151 offset:18432
	ds_read_b128 v[196:199], v250 offset:18432
	ds_read_b128 v[200:203], v151 offset:20480
	ds_read_b128 v[204:207], v250 offset:20480
	global_load_lds_dwordx4 v128, s[16:17]
	s_add_i32 m0, s51, 0x2000
	s_add_u32 s52, s16, 0x404000
	s_addc_u32 s53, s17, 0
	s_add_i32 s51, s42, s25
	global_load_lds_dwordx4 v130, s[16:17]
	s_mov_b32 m0, s51
	ds_read_b128 v[208:211], v151 offset:22528
	global_load_lds_dwordx4 v128, s[52:53]
	s_add_i32 m0, s51, 0x2000
	ds_read_b128 v[212:215], v250 offset:22528
	global_load_lds_dwordx4 v130, s[52:53]
	s_waitcnt vmcnt(6) lgkmcnt(0)
	s_setprio 2
	s_barrier
	v_mfma_f32_16x16x32_bf16 v[60:63], v[140:143], v[184:187], v[60:63]
	v_mfma_f32_16x16x32_bf16 v[60:63], v[156:159], v[188:191], v[60:63]
	v_mfma_f32_16x16x32_bf16 v[56:59], v[160:163], v[184:187], v[56:59]
	v_mfma_f32_16x16x32_bf16 v[56:59], v[164:167], v[188:191], v[56:59]
	v_mfma_f32_16x16x32_bf16 v[44:47], v[140:143], v[192:195], v[44:47]
	v_mfma_f32_16x16x32_bf16 v[44:47], v[156:159], v[196:199], v[44:47]
	v_mfma_f32_16x16x32_bf16 v[40:43], v[160:163], v[192:195], v[40:43]
	v_mfma_f32_16x16x32_bf16 v[40:43], v[164:167], v[196:199], v[40:43]
	v_mfma_f32_16x16x32_bf16 v[28:31], v[140:143], v[200:203], v[28:31]
	v_mfma_f32_16x16x32_bf16 v[28:31], v[156:159], v[204:207], v[28:31]
	v_mfma_f32_16x16x32_bf16 v[24:27], v[160:163], v[200:203], v[24:27]
	v_mfma_f32_16x16x32_bf16 v[24:27], v[164:167], v[204:207], v[24:27]
	v_mfma_f32_16x16x32_bf16 v[12:15], v[140:143], v[208:211], v[12:15]
	v_mfma_f32_16x16x32_bf16 v[12:15], v[156:159], v[212:215], v[12:15]
	v_mfma_f32_16x16x32_bf16 v[8:11], v[160:163], v[208:211], v[8:11]
	v_mfma_f32_16x16x32_bf16 v[8:11], v[164:167], v[212:215], v[8:11]
	s_setprio 0
	s_setprio 2
	v_mfma_f32_16x16x32_bf16 v[52:55], v[168:171], v[184:187], v[52:55]
	v_mfma_f32_16x16x32_bf16 v[52:55], v[172:175], v[188:191], v[52:55]
	v_mfma_f32_16x16x32_bf16 v[48:51], v[176:179], v[184:187], v[48:51]
	v_mfma_f32_16x16x32_bf16 v[48:51], v[180:183], v[188:191], v[48:51]
	v_mfma_f32_16x16x32_bf16 v[36:39], v[168:171], v[192:195], v[36:39]
	v_mfma_f32_16x16x32_bf16 v[36:39], v[172:175], v[196:199], v[36:39]
	v_mfma_f32_16x16x32_bf16 v[32:35], v[176:179], v[192:195], v[32:35]
	v_mfma_f32_16x16x32_bf16 v[32:35], v[180:183], v[196:199], v[32:35]
	v_mfma_f32_16x16x32_bf16 v[20:23], v[168:171], v[200:203], v[20:23]
	v_mfma_f32_16x16x32_bf16 v[20:23], v[172:175], v[204:207], v[20:23]
	v_mfma_f32_16x16x32_bf16 v[16:19], v[176:179], v[200:203], v[16:19]
	v_mfma_f32_16x16x32_bf16 v[16:19], v[180:183], v[204:207], v[16:19]
	v_mfma_f32_16x16x32_bf16 v[4:7], v[168:171], v[208:211], v[4:7]
	v_mfma_f32_16x16x32_bf16 v[4:7], v[172:175], v[212:215], v[4:7]
	s_setprio 3
	s_barrier
; #define PG8_STAGE(bufoff, gbase, voff) do { _Pragma("unroll") for (int _i = 0; _i < 2; ++_i) \
;         __builtin_amdgcn_global_load_lds((const unsigned*)((const char*)(gbase) + (voff)[_i]), (LAS unsigned*)(lds + (bufoff) + ldsw + _i * 8192), 16, 0, 0); } while (0)
; #define PG8_LDA(dst, b, h) do { _Pragma("unroll") for (int m = 0; m < 4; ++m) _Pragma("unroll") for (int k = 0; k < 2; ++k) dst[m][k] = *(const LAS bf16x8*)(lds + PG8_SA(b, h) + aoff + m * 2048 + k * 1024); } while (0)
; #define PG8_LDB(dst, b, h) do { _Pragma("unroll") for (int n = 0; n < 2; ++n) _Pragma("unroll") for (int k = 0; k < 2; ++k) dst[n][k] = *(const LAS bf16x8*)(lds + PG8_SB(b, h) + boff + n * 2048 + k * 1024); } while (0)
; #define PG8_MMA(ai, bj, At, Bt) do { __builtin_amdgcn_s_setprio(3); _Pragma("unroll") for (int m = 0; m < 4; ++m) _Pragma("unroll") for (int n = 0; n < 2; ++n) _Pragma("unroll") for (int k = 0; k < 2; ++k) \
;         acc[ai][bj][m][n] = __builtin_amdgcn_mfma_f32_16x16x32_bf16(Bt[n][k], At[m][k], acc[ai][bj][m][n], 0, 0, 0); __builtin_amdgcn_s_setprio(0); } while (0)
; #define PG8_WAIT_V(n) asm volatile("s_waitcnt vmcnt(" #n ")" ::: "memory")
; #define PG8_WAIT_L(n) asm volatile("s_waitcnt lgkmcnt(" #n ")" ::: "memory")
; template <class Epi, class Sched, bool ALIGN_EPI = false, bool SP2 = false>
; __device__ __forceinline__ void gemm_phase(LAS unsigned char* lds, const Gemm g, const Sched& S, const Epi& E) {
;     ...
;             PG8_WAIT_V(8); PG8_WAIT_L(0); PG8_BAR; PG8_MMA(0, 0, At, B0); PG8_MMA(0, 1, At, B1); PG8_BAR; PG8_SCHED;
;             PG8_LDA(At, 0, 1); PG8_STAGE(PG8_SB(0, 0), b2, voffB); PG8_STAGE(PG8_SB(0, 1), b2 + hsB, voffB); PG8_STAGE(PG8_SA(0, 0), a2, voffA);
;             PG8_WAIT_V(8); PG8_WAIT_L(0); PG8_BAR; PG8_MMA(1, 0, At, B0); PG8_MMA(1, 1, At, B1); PG8_BAR; PG8_SCHED;
;             PG8_LDB(B0, 1, 0); PG8_LDB(B1, 1, 1); PG8_SCHED; PG8_LDA(At, 1, 0); PG8_STAGE(PG8_SA(0, 1), a2 + hsA, voffA);
;             PG8_WAIT_V(8); PG8_WAIT_L(0); PG8_BAR; PG8_MMA(0, 0, At, B0); PG8_MMA(0, 1, At, B1); PG8_BAR; PG8_SCHED;
;             PG8_LDA(At, 1, 1); PG8_STAGE(PG8_SB(1, 0), b3, voffB); PG8_STAGE(PG8_SB(1, 1), b3 + hsB, voffB); PG8_STAGE(PG8_SA(1, 0), a3, voffA);
;             PG8_WAIT_V(8); PG8_WAIT_L(0); PG8_BAR; PG8_MMA(1, 0, At, B0); PG8_MMA(1, 1, At, B1); PG8_BAR; PG8_SCHED;
;     ...
;         if constexpr (ALIGN_EPI) { if (wr == 0) PG8_BAR; }
	v_mfma_f32_16x16x32_bf16 v[0:3], v[176:179], v[208:211], v[0:3]
	v_mfma_f32_16x16x32_bf16 v[0:3], v[180:183], v[212:215], v[0:3]
	s_setprio 0
	s_add_i32 s51, 0, 0x18000
	s_add_i32 s52, 0, 0x1c000
	ds_read_b128 v[140:143], v246
	ds_read_b128 v[156:159], v247
	ds_read_b128 v[160:163], v246 offset:2048
	ds_read_b128 v[164:167], v247 offset:2048
	ds_read_b128 v[168:171], v248
	ds_read_b128 v[172:175], v249
	ds_read_b128 v[176:179], v248 offset:2048
	ds_read_b128 v[180:183], v249 offset:2048
	s_mov_b32 m0, s26
	ds_read_b128 v[204:207], v250 offset:36864
	global_load_lds_dwordx4 v128, s[20:21]
	s_mov_b32 m0, s27
	ds_read_b128 v[208:211], v151 offset:38912
	global_load_lds_dwordx4 v130, s[20:21]
	s_add_u32 s20, s20, 0x404000
	s_addc_u32 s21, s21, 0
	s_mov_b32 m0, s30
	ds_read_b128 v[184:187], v151 offset:32768
	ds_read_b128 v[188:191], v250 offset:32768
	ds_read_b128 v[192:195], v151 offset:34816
	ds_read_b128 v[196:199], v250 offset:34816
	ds_read_b128 v[200:203], v151 offset:36864
	global_load_lds_dwordx4 v128, s[20:21]
	s_mov_b32 m0, s31
	ds_read_b128 v[212:215], v250 offset:38912
	global_load_lds_dwordx4 v130, s[20:21]
	s_waitcnt vmcnt(8) lgkmcnt(0)
	s_setprio 2
	s_barrier
	v_mfma_f32_16x16x32_bf16 v[124:127], v[140:143], v[184:187], v[124:127]
	v_mfma_f32_16x16x32_bf16 v[124:127], v[156:159], v[188:191], v[124:127]
	v_mfma_f32_16x16x32_bf16 v[120:123], v[160:163], v[184:187], v[120:123]
	v_mfma_f32_16x16x32_bf16 v[120:123], v[164:167], v[188:191], v[120:123]
	v_mfma_f32_16x16x32_bf16 v[108:111], v[140:143], v[192:195], v[108:111]
	v_mfma_f32_16x16x32_bf16 v[108:111], v[156:159], v[196:199], v[108:111]
	v_mfma_f32_16x16x32_bf16 v[104:107], v[160:163], v[192:195], v[104:107]
	v_mfma_f32_16x16x32_bf16 v[104:107], v[164:167], v[196:199], v[104:107]
	v_mfma_f32_16x16x32_bf16 v[92:95], v[140:143], v[200:203], v[92:95]
	v_mfma_f32_16x16x32_bf16 v[92:95], v[156:159], v[204:207], v[92:95]
	v_mfma_f32_16x16x32_bf16 v[88:91], v[160:163], v[200:203], v[88:91]
	v_mfma_f32_16x16x32_bf16 v[88:91], v[164:167], v[204:207], v[88:91]
	v_mfma_f32_16x16x32_bf16 v[76:79], v[140:143], v[208:211], v[76:79]
	v_mfma_f32_16x16x32_bf16 v[76:79], v[156:159], v[212:215], v[76:79]
	v_mfma_f32_16x16x32_bf16 v[72:75], v[160:163], v[208:211], v[72:75]
	v_mfma_f32_16x16x32_bf16 v[72:75], v[164:167], v[212:215], v[72:75]
	s_setprio 0
	s_setprio 2
	v_mfma_f32_16x16x32_bf16 v[116:119], v[168:171], v[184:187], v[116:119]
	v_mfma_f32_16x16x32_bf16 v[116:119], v[172:175], v[188:191], v[116:119]
	v_mfma_f32_16x16x32_bf16 v[112:115], v[176:179], v[184:187], v[112:115]
	v_mfma_f32_16x16x32_bf16 v[112:115], v[180:183], v[188:191], v[112:115]
	v_mfma_f32_16x16x32_bf16 v[100:103], v[168:171], v[192:195], v[100:103]
	v_mfma_f32_16x16x32_bf16 v[100:103], v[172:175], v[196:199], v[100:103]
	v_mfma_f32_16x16x32_bf16 v[96:99], v[176:179], v[192:195], v[96:99]
	v_mfma_f32_16x16x32_bf16 v[96:99], v[180:183], v[196:199], v[96:99]
	v_mfma_f32_16x16x32_bf16 v[84:87], v[168:171], v[200:203], v[84:87]
	v_mfma_f32_16x16x32_bf16 v[84:87], v[172:175], v[204:207], v[84:87]
	v_mfma_f32_16x16x32_bf16 v[80:83], v[176:179], v[200:203], v[80:83]
	v_mfma_f32_16x16x32_bf16 v[80:83], v[180:183], v[204:207], v[80:83]
	v_mfma_f32_16x16x32_bf16 v[68:71], v[168:171], v[208:211], v[68:71]
	v_mfma_f32_16x16x32_bf16 v[68:71], v[172:175], v[212:215], v[68:71]
	s_setprio 3
	s_barrier
	v_mfma_f32_16x16x32_bf16 v[64:67], v[176:179], v[208:211], v[64:67]
	v_mfma_f32_16x16x32_bf16 v[64:67], v[180:183], v[212:215], v[64:67]
	s_setprio 0
	s_add_i32 s20, s51, s25
	s_add_u32 s100, s16, s8
	s_addc_u32 s101, s17, s9
	s_mov_b32 m0, s20
	ds_read_b128 v[184:187], v151 offset:49152
	ds_read_b128 v[188:191], v250 offset:49152
	ds_read_b128 v[192:195], v151 offset:51200
	ds_read_b128 v[196:199], v250 offset:51200
	ds_read_b128 v[200:203], v151 offset:53248
	ds_read_b128 v[204:207], v250 offset:53248
	global_load_lds_dwordx4 v128, s[100:101]
	s_add_i32 m0, s20, 0x2000
	s_add_u32 s16, s16, 0x404080
	s_addc_u32 s17, s17, 0
	s_add_i32 s20, s52, s25
	global_load_lds_dwordx4 v130, s[100:101]
	s_mov_b32 m0, s20
	ds_read_b128 v[208:211], v151 offset:55296
	global_load_lds_dwordx4 v128, s[16:17]
	s_add_i32 m0, s20, 0x2000
	ds_read_b128 v[212:215], v250 offset:55296
	global_load_lds_dwordx4 v130, s[16:17]
	s_waitcnt vmcnt(6) lgkmcnt(0)
	s_setprio 2
	s_barrier
	v_mfma_f32_16x16x32_bf16 v[60:63], v[140:143], v[184:187], v[60:63]
	v_mfma_f32_16x16x32_bf16 v[60:63], v[156:159], v[188:191], v[60:63]
	v_mfma_f32_16x16x32_bf16 v[56:59], v[160:163], v[184:187], v[56:59]
	v_mfma_f32_16x16x32_bf16 v[56:59], v[164:167], v[188:191], v[56:59]
	v_mfma_f32_16x16x32_bf16 v[44:47], v[140:143], v[192:195], v[44:47]
	v_mfma_f32_16x16x32_bf16 v[44:47], v[156:159], v[196:199], v[44:47]
	v_mfma_f32_16x16x32_bf16 v[40:43], v[160:163], v[192:195], v[40:43]
	v_mfma_f32_16x16x32_bf16 v[40:43], v[164:167], v[196:199], v[40:43]
	v_mfma_f32_16x16x32_bf16 v[28:31], v[140:143], v[200:203], v[28:31]
	v_mfma_f32_16x16x32_bf16 v[28:31], v[156:159], v[204:207], v[28:31]
	v_mfma_f32_16x16x32_bf16 v[24:27], v[160:163], v[200:203], v[24:27]
	v_mfma_f32_16x16x32_bf16 v[24:27], v[164:167], v[204:207], v[24:27]
	v_mfma_f32_16x16x32_bf16 v[12:15], v[140:143], v[208:211], v[12:15]
	v_mfma_f32_16x16x32_bf16 v[12:15], v[156:159], v[212:215], v[12:15]
	v_mfma_f32_16x16x32_bf16 v[8:11], v[160:163], v[208:211], v[8:11]
	v_mfma_f32_16x16x32_bf16 v[8:11], v[164:167], v[212:215], v[8:11]
	s_setprio 0
	s_setprio 2
	v_mfma_f32_16x16x32_bf16 v[52:55], v[168:171], v[184:187], v[52:55]
	v_mfma_f32_16x16x32_bf16 v[52:55], v[172:175], v[188:191], v[52:55]
	v_mfma_f32_16x16x32_bf16 v[48:51], v[176:179], v[184:187], v[48:51]
	v_mfma_f32_16x16x32_bf16 v[48:51], v[180:183], v[188:191], v[48:51]
	v_mfma_f32_16x16x32_bf16 v[36:39], v[168:171], v[192:195], v[36:39]
	v_mfma_f32_16x16x32_bf16 v[36:39], v[172:175], v[196:199], v[36:39]
	v_mfma_f32_16x16x32_bf16 v[32:35], v[176:179], v[192:195], v[32:35]
	v_mfma_f32_16x16x32_bf16 v[32:35], v[180:183], v[196:199], v[32:35]
	v_mfma_f32_16x16x32_bf16 v[20:23], v[168:171], v[200:203], v[20:23]
	v_mfma_f32_16x16x32_bf16 v[20:23], v[172:175], v[204:207], v[20:23]
	v_mfma_f32_16x16x32_bf16 v[16:19], v[176:179], v[200:203], v[16:19]
	v_mfma_f32_16x16x32_bf16 v[16:19], v[180:183], v[204:207], v[16:19]
	v_mfma_f32_16x16x32_bf16 v[4:7], v[168:171], v[208:211], v[4:7]
	v_mfma_f32_16x16x32_bf16 v[4:7], v[172:175], v[212:215], v[4:7]
	s_setprio 3
	s_barrier
	v_mfma_f32_16x16x32_bf16 v[0:3], v[176:179], v[208:211], v[0:3]
	v_mfma_f32_16x16x32_bf16 v[0:3], v[180:183], v[212:215], v[0:3]
	s_setprio 0
	s_add_i32 s50, s50, 2
	s_add_u32 s14, s14, 0x100
	s_addc_u32 s15, s15, 0
	s_add_u32 s48, s48, 0x100
	s_addc_u32 s49, s49, 0
	s_cmpk_gt_u32 s50, 0xfd
	s_cbranch_scc0 .LBB0_350
	s_and_b64 vcc, exec, s[10:11]
	s_cbranch_vccz .LBB0_353
	s_barrier
